# residual epilogues (P6, P8): flat->global loads/stores; cross-lane row sums via v_permlane16/32_swap instead of ds_bpermute round trips
# baseline (speedup 1.0000x reference)
;     __device__ __forceinline__ void operator()(const f32x4 (&acc)[2][2][4][2], const Unit& u, int wr, int wc, int fr, int fq) const {
;     ...
;         u32x4 bw[2][4][2];
;         if (!base32) {
; #pragma unroll
;             for (int ai = 0; ai < 2; ++ai)
; #pragma unroll
;                 for (int m = 0; m < 4; ++m)
; #pragma unroll
;                     for (int bj = 0; bj < 2; ++bj) bw[ai][m][bj] = *(const u32x4*)(XN + (size_t)(row0 + ai * 128 + m * 16) * DM + col0 + bj * 128);
;         }
.LBB0_703:
	v_lshl_or_b32 v224, s92, 8, v246
	v_or_b32_e32 v230, 16, v222
	v_or_b32_e32 v228, 32, v222
	v_or_b32_e32 v226, 48, v222
	v_ashrrev_i32_e32 v225, 31, v224
	s_andn2_b64 vcc, exec, s[30:31]
	v_ashrrev_i32_e32 v231, 31, v230
	v_ashrrev_i32_e32 v229, 31, v228
	v_ashrrev_i32_e32 v227, 31, v226
	s_cbranch_vccnz .LBB0_705
	v_lshl_add_u64 v[64:65], v[224:225], 1, s[54:55]
	v_lshlrev_b64 v[66:67], 11, v[222:223]
	v_lshlrev_b64 v[76:77], 11, v[230:231]
	v_lshl_add_u64 v[66:67], v[64:65], 0, v[66:67]
	v_lshl_add_u64 v[76:77], v[64:65], 0, v[76:77]
	global_load_dwordx4 v[188:191], v[66:67], off
	global_load_dwordx4 v[184:187], v[66:67], off offset:256
	global_load_dwordx4 v[180:183], v[76:77], off
	global_load_dwordx4 v[176:179], v[76:77], off offset:256
	v_lshlrev_b64 v[76:77], 11, v[228:229]
	v_lshl_add_u64 v[76:77], v[64:65], 0, v[76:77]
	v_readlane_b32 s72, v255, 48
	global_load_dwordx4 v[172:175], v[76:77], off
	global_load_dwordx4 v[168:171], v[76:77], off offset:256
	v_lshlrev_b64 v[76:77], 11, v[226:227]
	v_readlane_b32 s74, v255, 50
	v_lshl_add_u64 v[64:65], v[64:65], 0, v[76:77]
	s_mov_b32 s23, 0x48000
	v_add_co_u32_e32 v76, vcc, s74, v66
	global_load_dwordx4 v[164:167], v[64:65], off
	global_load_dwordx4 v[160:163], v[64:65], off offset:256
	v_addc_co_u32_e32 v77, vcc, 0, v67, vcc
	v_lshl_add_u64 v[64:65], v[66:67], 0, s[18:19]
	global_load_dwordx4 v[148:151], v[76:77], off
	global_load_dwordx4 v[136:139], v[64:65], off offset:256
	v_add_co_u32_e32 v76, vcc, s23, v66
	s_mov_b32 s23, 0x50000
	s_nop 0
	v_addc_co_u32_e32 v77, vcc, 0, v67, vcc
	v_lshl_add_u64 v[64:65], v[66:67], 0, s[64:65]
	global_load_dwordx4 v[124:127], v[76:77], off
	global_load_dwordx4 v[112:115], v[64:65], off offset:256
	v_add_co_u32_e32 v76, vcc, s23, v66
	v_lshl_add_u64 v[64:65], v[66:67], 0, s[66:67]
	s_nop 0
	v_addc_co_u32_e32 v77, vcc, 0, v67, vcc
	s_mov_b32 s23, 0x58000
	global_load_dwordx4 v[100:103], v[76:77], off
	global_load_dwordx4 v[88:91], v[64:65], off offset:256
	v_lshl_add_u64 v[64:65], v[66:67], 0, s[68:69]
	v_add_co_u32_e32 v66, vcc, s23, v66
	v_readlane_b32 s73, v255, 49
	s_nop 0
	v_addc_co_u32_e32 v67, vcc, 0, v67, vcc
	global_load_dwordx4 v[76:79], v[66:67], off
	s_nop 0
	global_load_dwordx4 v[64:67], v[64:65], off offset:256
	v_readlane_b32 s75, v255, 51

; __device__ __forceinline__ u32x4 pack8(f32x4 v0, f32x4 v1) { u32x4 w; w.x = pk2(v0[0], v0[1]); w.y = pk2(v0[2], v0[3]); w.z = pk2(v1[0], v1[1]); w.w = pk2(v1[2], v1[3]); return w; }
;     __device__ __forceinline__ void operator()(const f32x4 (&acc)[2][2][4][2], const Unit& u, int wr, int wc, int fr, int fq) const {
;     ...
;                 const int row = row0 + ai * 128 + m * 16; const size_t off = (size_t)row * DM + col0; float ss = 0.f;
; #pragma unroll
;                 for (int bj = 0; bj < 2; ++bj) {
;                     f32x4 b0, b1;
;                     if (base32) { b0 = __builtin_nontemporal_load((const f32x4*)(base32 + off + bj * 128)); b1 = __builtin_nontemporal_load((const f32x4*)(base32 + off + bj * 128 + 4)); }
;                     else { const u32x4 w = bw[ai][m][bj]; b0 = (f32x4){bflo(w.x), bfhi(w.x), bflo(w.y), bfhi(w.y)}; b1 = (f32x4){bflo(w.z), bfhi(w.z), bflo(w.w), bfhi(w.w)}; }
;                     const f32x4 x0 = b0 + acc[ai][bj][m][0], x1 = b1 + acc[ai][bj][m][1];
;                     if (out32) { __builtin_nontemporal_store(x0, (f32x4*)(out32 + off + bj * 128)); __builtin_nontemporal_store(x1, (f32x4*)(out32 + off + bj * 128 + 4)); }
;                     else *(u32x4*)(XN + off + bj * 128) = pack8(x0, x1);
.LBB0_708:
	s_waitcnt lgkmcnt(0)
	v_pk_add_f32 v[190:191], v[158:159], v[194:195]
	v_pk_add_f32 v[194:195], v[156:157], v[192:193]
	v_pk_add_f32 v[192:193], v[154:155], v[198:199]
	v_pk_add_f32 v[196:197], v[152:153], v[196:197]
	v_cvt_pk_bf16_f32 v152, v194, v195
	v_cvt_pk_bf16_f32 v153, v190, v191
	v_cvt_pk_bf16_f32 v154, v196, v197
	v_cvt_pk_bf16_f32 v155, v192, v193
	v_lshl_add_u64 v[188:189], v[234:235], 1, s[54:55]
	s_and_b64 vcc, exec, s[44:45]
	global_store_dwordx4 v[188:189], v[152:155], off
	s_cbranch_vccnz .LBB0_773
	global_load_dwordx4 v[156:159], v[232:233], off offset:528 nt
	global_load_dwordx4 v[152:155], v[232:233], off offset:512 nt
	s_waitcnt vmcnt(0)
	s_cbranch_execnz .LBB0_711

; __device__ __forceinline__ u32x4 pack8(f32x4 v0, f32x4 v1) { u32x4 w; w.x = pk2(v0[0], v0[1]); w.y = pk2(v0[2], v0[3]); w.z = pk2(v1[0], v1[1]); w.w = pk2(v1[2], v1[3]); return w; }
;     __device__ __forceinline__ void operator()(const f32x4 (&acc)[2][2][4][2], const Unit& u, int wr, int wc, int fr, int fq) const {
;     ...
;                     const f32x4 x0 = b0 + acc[ai][bj][m][0], x1 = b1 + acc[ai][bj][m][1];
;                     if (out32) { __builtin_nontemporal_store(x0, (f32x4*)(out32 + off + bj * 128)); __builtin_nontemporal_store(x1, (f32x4*)(out32 + off + bj * 128 + 4)); }
;                     else *(u32x4*)(XN + off + bj * 128) = pack8(x0, x1);
;                     ss += ((x0[0] * x0[0] + x0[1] * x0[1]) + (x0[2] * x0[2] + x0[3] * x0[3])) + ((x1[0] * x1[0] + x1[1] * x1[1]) + (x1[2] * x1[2] + x1[3] * x1[3]));
;                 }
;                 ss += __shfl_xor(ss, 16); ss += __shfl_xor(ss, 32);
;                 if (fq == 0) part[(size_t)row * 16 + u.pn * 4 + wc] = ss;
.LBB0_711:
	v_mul_f32_e32 v184, v195, v195
	v_mul_f32_e32 v185, v191, v191
	v_fmac_f32_e32 v184, v194, v194
	v_fmac_f32_e32 v185, v190, v190
	v_pk_add_f32 v[146:147], v[146:147], v[154:155]
	v_pk_add_f32 v[144:145], v[144:145], v[152:153]
	v_add_f32_e32 v184, v184, v185
	v_mul_f32_e32 v185, v197, v197
	v_mul_f32_e32 v186, v193, v193
	v_pk_add_f32 v[154:155], v[140:141], v[156:157]
	v_mul_f32_e32 v140, v145, v145
	v_mul_f32_e32 v141, v147, v147
	v_fmac_f32_e32 v185, v196, v196
	v_fmac_f32_e32 v186, v192, v192
	v_pk_add_f32 v[152:153], v[142:143], v[158:159]
	v_fmac_f32_e32 v140, v144, v144
	v_fmac_f32_e32 v141, v146, v146
	v_add_f32_e32 v185, v185, v186
	v_and_b32_e32 v186, 64, v243
	v_add_f32_e32 v140, v140, v141
	v_mul_f32_e32 v141, v155, v155
	v_mul_f32_e32 v142, v153, v153
	v_add_f32_e32 v185, v184, v185
	v_xor_b32_e32 v184, 16, v243
	v_add_u32_e32 v186, 64, v186
	v_fmac_f32_e32 v141, v154, v154
	v_fmac_f32_e32 v142, v152, v152
	v_cmp_lt_i32_e32 vcc, v184, v186
	v_add_f32_e32 v141, v141, v142
	v_add_f32_e32 v140, v140, v141
	v_cndmask_b32_e32 v184, v243, v184, vcc
	v_lshlrev_b32_e32 v184, 2, v184
	v_add_f32_e32 v140, v185, v140
	v_xor_b32_e32 v187, 32, v243
	v_cmp_lt_i32_e32 vcc, v187, v186
	s_lshl_b32 s92, s92, 2
	s_ashr_i32 s93, s92, 31
	v_cndmask_b32_e32 v186, v243, v187, vcc
	v_lshlrev_b32_e32 v158, 2, v186
	v_mov_b32_e32 v141, v140
	s_nop 1
	v_permlane16_swap_b32_e32 v140, v141
	v_add_f32_e32 v140, v140, v141
	v_mov_b32_e32 v141, v140
	s_nop 1
	v_permlane32_swap_b32_e32 v140, v141
	v_cvt_pk_bf16_f32 v142, v144, v145
	v_cvt_pk_bf16_f32 v143, v146, v147
	v_cvt_pk_bf16_f32 v144, v154, v155
	v_cvt_pk_bf16_f32 v145, v152, v153
	global_store_dwordx4 v[188:189], v[142:145], off offset:256
	s_and_saveexec_b64 s[30:31], s[40:41]
	s_cbranch_execz .LBB0_713
	v_lshlrev_b64 v[142:143], 6, v[222:223]
	v_lshl_add_u64 v[142:143], s[62:63], 0, v[142:143]
	v_lshl_add_u64 v[142:143], s[92:93], 2, v[142:143]
	s_lshl_b32 s58, s53, 2
	v_lshl_add_u64 v[142:143], v[142:143], 0, s[58:59]
	s_waitcnt lgkmcnt(0)
	v_add_f32_e32 v140, v140, v141
	global_store_dword v[142:143], v140, off

; __device__ __forceinline__ u32x4 pack8(f32x4 v0, f32x4 v1) { u32x4 w; w.x = pk2(v0[0], v0[1]); w.y = pk2(v0[2], v0[3]); w.z = pk2(v1[0], v1[1]); w.w = pk2(v1[2], v1[3]); return w; }
;     __device__ __forceinline__ void operator()(const f32x4 (&acc)[2][2][4][2], const Unit& u, int wr, int wc, int fr, int fq) const {
;     ...
;                 const int row = row0 + ai * 128 + m * 16; const size_t off = (size_t)row * DM + col0; float ss = 0.f;
; #pragma unroll
;                 for (int bj = 0; bj < 2; ++bj) {
;                     f32x4 b0, b1;
;                     if (base32) { b0 = __builtin_nontemporal_load((const f32x4*)(base32 + off + bj * 128)); b1 = __builtin_nontemporal_load((const f32x4*)(base32 + off + bj * 128 + 4)); }
;                     else { const u32x4 w = bw[ai][m][bj]; b0 = (f32x4){bflo(w.x), bfhi(w.x), bflo(w.y), bfhi(w.y)}; b1 = (f32x4){bflo(w.z), bfhi(w.z), bflo(w.w), bfhi(w.w)}; }
;                     const f32x4 x0 = b0 + acc[ai][bj][m][0], x1 = b1 + acc[ai][bj][m][1];
;                     if (out32) { __builtin_nontemporal_store(x0, (f32x4*)(out32 + off + bj * 128)); __builtin_nontemporal_store(x1, (f32x4*)(out32 + off + bj * 128 + 4)); }
;                     else *(u32x4*)(XN + off + bj * 128) = pack8(x0, x1);
.LBB0_716:
	v_pk_add_f32 v[142:143], v[134:135], v[142:143]
	v_pk_add_f32 v[156:157], v[132:133], v[140:141]
	v_pk_add_f32 v[146:147], v[130:131], v[146:147]
	v_pk_add_f32 v[144:145], v[128:129], v[144:145]
	v_cvt_pk_bf16_f32 v128, v156, v157
	v_cvt_pk_bf16_f32 v129, v142, v143
	v_cvt_pk_bf16_f32 v130, v144, v145
	v_cvt_pk_bf16_f32 v131, v146, v147
	v_lshl_add_u64 v[140:141], v[154:155], 1, s[54:55]
	s_and_b64 vcc, exec, s[44:45]
	global_store_dwordx4 v[140:141], v[128:131], off
	s_cbranch_vccnz .LBB0_775
	global_load_dwordx4 v[132:135], v[152:153], off offset:528 nt
	global_load_dwordx4 v[128:131], v[152:153], off offset:512 nt
	s_waitcnt vmcnt(0)
	s_cbranch_execnz .LBB0_719

; __device__ __forceinline__ u32x4 pack8(f32x4 v0, f32x4 v1) { u32x4 w; w.x = pk2(v0[0], v0[1]); w.y = pk2(v0[2], v0[3]); w.z = pk2(v1[0], v1[1]); w.w = pk2(v1[2], v1[3]); return w; }
;     __device__ __forceinline__ void operator()(const f32x4 (&acc)[2][2][4][2], const Unit& u, int wr, int wc, int fr, int fq) const {
;     ...
;                     const f32x4 x0 = b0 + acc[ai][bj][m][0], x1 = b1 + acc[ai][bj][m][1];
;                     if (out32) { __builtin_nontemporal_store(x0, (f32x4*)(out32 + off + bj * 128)); __builtin_nontemporal_store(x1, (f32x4*)(out32 + off + bj * 128 + 4)); }
;                     else *(u32x4*)(XN + off + bj * 128) = pack8(x0, x1);
;                     ss += ((x0[0] * x0[0] + x0[1] * x0[1]) + (x0[2] * x0[2] + x0[3] * x0[3])) + ((x1[0] * x1[0] + x1[1] * x1[1]) + (x1[2] * x1[2] + x1[3] * x1[3]));
;                 }
;                 ss += __shfl_xor(ss, 16); ss += __shfl_xor(ss, 32);
;                 if (fq == 0) part[(size_t)row * 16 + u.pn * 4 + wc] = ss;
.LBB0_719:
	v_mul_f32_e32 v152, v157, v157
	v_mul_f32_e32 v143, v143, v143
	v_pk_add_f32 v[122:123], v[122:123], v[130:131]
	v_pk_add_f32 v[120:121], v[120:121], v[128:129]
	v_fmac_f32_e32 v152, v156, v156
	v_fmac_f32_e32 v143, v142, v142
	v_pk_add_f32 v[130:131], v[116:117], v[132:133]
	v_mul_f32_e32 v116, v121, v121
	v_mul_f32_e32 v117, v123, v123
	v_add_f32_e32 v142, v152, v143
	v_mul_f32_e32 v143, v145, v145
	v_pk_add_f32 v[128:129], v[118:119], v[134:135]
	v_fmac_f32_e32 v116, v120, v120
	v_fmac_f32_e32 v117, v122, v122
	v_fmac_f32_e32 v143, v144, v144
	v_mul_f32_e32 v144, v147, v147
	v_add_f32_e32 v116, v116, v117
	v_mul_f32_e32 v117, v131, v131
	v_mul_f32_e32 v118, v129, v129
	v_fmac_f32_e32 v144, v146, v146
	v_fmac_f32_e32 v117, v130, v130
	v_fmac_f32_e32 v118, v128, v128
	v_add_f32_e32 v143, v143, v144
	v_add_f32_e32 v117, v117, v118
	v_add_f32_e32 v142, v142, v143
	v_add_f32_e32 v116, v116, v117
	v_add_f32_e32 v116, v142, v116
	v_cvt_pk_bf16_f32 v118, v120, v121
	v_cvt_pk_bf16_f32 v119, v122, v123
	v_cvt_pk_bf16_f32 v120, v130, v131
	v_cvt_pk_bf16_f32 v121, v128, v129
	v_mov_b32_e32 v117, v116
	s_nop 1
	v_permlane16_swap_b32_e32 v116, v117
	v_add_f32_e32 v116, v116, v117
	v_mov_b32_e32 v117, v116
	s_nop 1
	v_permlane32_swap_b32_e32 v116, v117
	global_store_dwordx4 v[140:141], v[118:121], off offset:256
	s_and_saveexec_b64 s[30:31], s[40:41]
	s_cbranch_execz .LBB0_721
	v_lshlrev_b64 v[118:119], 6, v[230:231]
	v_lshl_add_u64 v[118:119], s[62:63], 0, v[118:119]
	v_lshl_add_u64 v[118:119], s[92:93], 2, v[118:119]
	s_lshl_b32 s58, s53, 2
	v_lshl_add_u64 v[118:119], v[118:119], 0, s[58:59]
	s_waitcnt lgkmcnt(0)
	v_add_f32_e32 v116, v116, v117
	global_store_dword v[118:119], v116, off

; __device__ __forceinline__ u32x4 pack8(f32x4 v0, f32x4 v1) { u32x4 w; w.x = pk2(v0[0], v0[1]); w.y = pk2(v0[2], v0[3]); w.z = pk2(v1[0], v1[1]); w.w = pk2(v1[2], v1[3]); return w; }
;     __device__ __forceinline__ void operator()(const f32x4 (&acc)[2][2][4][2], const Unit& u, int wr, int wc, int fr, int fq) const {
;     ...
;                 const int row = row0 + ai * 128 + m * 16; const size_t off = (size_t)row * DM + col0; float ss = 0.f;
; #pragma unroll
;                 for (int bj = 0; bj < 2; ++bj) {
;                     f32x4 b0, b1;
;                     if (base32) { b0 = __builtin_nontemporal_load((const f32x4*)(base32 + off + bj * 128)); b1 = __builtin_nontemporal_load((const f32x4*)(base32 + off + bj * 128 + 4)); }
;                     else { const u32x4 w = bw[ai][m][bj]; b0 = (f32x4){bflo(w.x), bfhi(w.x), bflo(w.y), bfhi(w.y)}; b1 = (f32x4){bflo(w.z), bfhi(w.z), bflo(w.w), bfhi(w.w)}; }
;                     const f32x4 x0 = b0 + acc[ai][bj][m][0], x1 = b1 + acc[ai][bj][m][1];
;                     if (out32) { __builtin_nontemporal_store(x0, (f32x4*)(out32 + off + bj * 128)); __builtin_nontemporal_store(x1, (f32x4*)(out32 + off + bj * 128 + 4)); }
;                     else *(u32x4*)(XN + off + bj * 128) = pack8(x0, x1);
.LBB0_724:
	v_pk_add_f32 v[118:119], v[110:111], v[118:119]
	v_pk_add_f32 v[132:133], v[108:109], v[116:117]
	v_pk_add_f32 v[122:123], v[106:107], v[122:123]
	v_pk_add_f32 v[120:121], v[104:105], v[120:121]
	v_cvt_pk_bf16_f32 v104, v132, v133
	v_cvt_pk_bf16_f32 v105, v118, v119
	v_cvt_pk_bf16_f32 v106, v120, v121
	v_cvt_pk_bf16_f32 v107, v122, v123
	v_lshl_add_u64 v[116:117], v[130:131], 1, s[54:55]
	s_and_b64 vcc, exec, s[44:45]
	global_store_dwordx4 v[116:117], v[104:107], off
	s_cbranch_vccnz .LBB0_777
	global_load_dwordx4 v[108:111], v[128:129], off offset:528 nt
	global_load_dwordx4 v[104:107], v[128:129], off offset:512 nt
	s_waitcnt vmcnt(0)
	s_cbranch_execnz .LBB0_727

; __device__ __forceinline__ u32x4 pack8(f32x4 v0, f32x4 v1) { u32x4 w; w.x = pk2(v0[0], v0[1]); w.y = pk2(v0[2], v0[3]); w.z = pk2(v1[0], v1[1]); w.w = pk2(v1[2], v1[3]); return w; }
;     __device__ __forceinline__ void operator()(const f32x4 (&acc)[2][2][4][2], const Unit& u, int wr, int wc, int fr, int fq) const {
;     ...
;                     const f32x4 x0 = b0 + acc[ai][bj][m][0], x1 = b1 + acc[ai][bj][m][1];
;                     if (out32) { __builtin_nontemporal_store(x0, (f32x4*)(out32 + off + bj * 128)); __builtin_nontemporal_store(x1, (f32x4*)(out32 + off + bj * 128 + 4)); }
;                     else *(u32x4*)(XN + off + bj * 128) = pack8(x0, x1);
;                     ss += ((x0[0] * x0[0] + x0[1] * x0[1]) + (x0[2] * x0[2] + x0[3] * x0[3])) + ((x1[0] * x1[0] + x1[1] * x1[1]) + (x1[2] * x1[2] + x1[3] * x1[3]));
;                 }
;                 ss += __shfl_xor(ss, 16); ss += __shfl_xor(ss, 32);
;                 if (fq == 0) part[(size_t)row * 16 + u.pn * 4 + wc] = ss;
.LBB0_727:
	v_mul_f32_e32 v128, v133, v133
	v_mul_f32_e32 v119, v119, v119
	v_pk_add_f32 v[98:99], v[98:99], v[106:107]
	v_pk_add_f32 v[96:97], v[96:97], v[104:105]
	v_fmac_f32_e32 v128, v132, v132
	v_fmac_f32_e32 v119, v118, v118
	v_pk_add_f32 v[106:107], v[92:93], v[108:109]
	v_mul_f32_e32 v92, v97, v97
	v_mul_f32_e32 v93, v99, v99
	v_add_f32_e32 v118, v128, v119
	v_mul_f32_e32 v119, v121, v121
	v_pk_add_f32 v[104:105], v[94:95], v[110:111]
	v_fmac_f32_e32 v92, v96, v96
	v_fmac_f32_e32 v93, v98, v98
	v_fmac_f32_e32 v119, v120, v120
	v_mul_f32_e32 v120, v123, v123
	v_add_f32_e32 v92, v92, v93
	v_mul_f32_e32 v93, v107, v107
	v_mul_f32_e32 v94, v105, v105
	v_fmac_f32_e32 v120, v122, v122
	v_fmac_f32_e32 v93, v106, v106
	v_fmac_f32_e32 v94, v104, v104
	v_add_f32_e32 v119, v119, v120
	v_add_f32_e32 v93, v93, v94
	v_add_f32_e32 v118, v118, v119
	v_add_f32_e32 v92, v92, v93
	v_add_f32_e32 v92, v118, v92
	v_cvt_pk_bf16_f32 v94, v96, v97
	v_cvt_pk_bf16_f32 v95, v98, v99
	v_cvt_pk_bf16_f32 v96, v106, v107
	v_cvt_pk_bf16_f32 v97, v104, v105
	v_mov_b32_e32 v93, v92
	s_nop 1
	v_permlane16_swap_b32_e32 v92, v93
	v_add_f32_e32 v92, v92, v93
	v_mov_b32_e32 v93, v92
	s_nop 1
	v_permlane32_swap_b32_e32 v92, v93
	global_store_dwordx4 v[116:117], v[94:97], off offset:256
	s_and_saveexec_b64 s[30:31], s[40:41]
	s_cbranch_execz .LBB0_729
	v_lshlrev_b64 v[94:95], 6, v[228:229]
	v_lshl_add_u64 v[94:95], s[62:63], 0, v[94:95]
	v_lshl_add_u64 v[94:95], s[92:93], 2, v[94:95]
	s_lshl_b32 s58, s53, 2
	v_lshl_add_u64 v[94:95], v[94:95], 0, s[58:59]
	s_waitcnt lgkmcnt(0)
	v_add_f32_e32 v92, v92, v93
	global_store_dword v[94:95], v92, off

; __device__ __forceinline__ u32x4 pack8(f32x4 v0, f32x4 v1) { u32x4 w; w.x = pk2(v0[0], v0[1]); w.y = pk2(v0[2], v0[3]); w.z = pk2(v1[0], v1[1]); w.w = pk2(v1[2], v1[3]); return w; }
;     __device__ __forceinline__ void operator()(const f32x4 (&acc)[2][2][4][2], const Unit& u, int wr, int wc, int fr, int fq) const {
;     ...
;                 const int row = row0 + ai * 128 + m * 16; const size_t off = (size_t)row * DM + col0; float ss = 0.f;
; #pragma unroll
;                 for (int bj = 0; bj < 2; ++bj) {
;                     f32x4 b0, b1;
;                     if (base32) { b0 = __builtin_nontemporal_load((const f32x4*)(base32 + off + bj * 128)); b1 = __builtin_nontemporal_load((const f32x4*)(base32 + off + bj * 128 + 4)); }
;                     else { const u32x4 w = bw[ai][m][bj]; b0 = (f32x4){bflo(w.x), bfhi(w.x), bflo(w.y), bfhi(w.y)}; b1 = (f32x4){bflo(w.z), bfhi(w.z), bflo(w.w), bfhi(w.w)}; }
;                     const f32x4 x0 = b0 + acc[ai][bj][m][0], x1 = b1 + acc[ai][bj][m][1];
;                     if (out32) { __builtin_nontemporal_store(x0, (f32x4*)(out32 + off + bj * 128)); __builtin_nontemporal_store(x1, (f32x4*)(out32 + off + bj * 128 + 4)); }
;                     else *(u32x4*)(XN + off + bj * 128) = pack8(x0, x1);
.LBB0_732:
	v_pk_add_f32 v[94:95], v[86:87], v[94:95]
	v_pk_add_f32 v[108:109], v[84:85], v[92:93]
	v_pk_add_f32 v[98:99], v[82:83], v[98:99]
	v_pk_add_f32 v[96:97], v[80:81], v[96:97]
	v_cvt_pk_bf16_f32 v80, v108, v109
	v_cvt_pk_bf16_f32 v81, v94, v95
	v_cvt_pk_bf16_f32 v82, v96, v97
	v_cvt_pk_bf16_f32 v83, v98, v99
	v_lshl_add_u64 v[92:93], v[106:107], 1, s[54:55]
	s_and_b64 vcc, exec, s[44:45]
	global_store_dwordx4 v[92:93], v[80:83], off
	s_cbranch_vccnz .LBB0_779
	global_load_dwordx4 v[84:87], v[104:105], off offset:528 nt
	global_load_dwordx4 v[80:83], v[104:105], off offset:512 nt
	s_waitcnt vmcnt(0)
	s_cbranch_execnz .LBB0_735

; __device__ __forceinline__ u32x4 pack8(f32x4 v0, f32x4 v1) { u32x4 w; w.x = pk2(v0[0], v0[1]); w.y = pk2(v0[2], v0[3]); w.z = pk2(v1[0], v1[1]); w.w = pk2(v1[2], v1[3]); return w; }
;     __device__ __forceinline__ void operator()(const f32x4 (&acc)[2][2][4][2], const Unit& u, int wr, int wc, int fr, int fq) const {
;     ...
;                     if (base32) { b0 = __builtin_nontemporal_load((const f32x4*)(base32 + off + bj * 128)); b1 = __builtin_nontemporal_load((const f32x4*)(base32 + off + bj * 128 + 4)); }
;                     else { const u32x4 w = bw[ai][m][bj]; b0 = (f32x4){bflo(w.x), bfhi(w.x), bflo(w.y), bfhi(w.y)}; b1 = (f32x4){bflo(w.z), bfhi(w.z), bflo(w.w), bfhi(w.w)}; }
;                     const f32x4 x0 = b0 + acc[ai][bj][m][0], x1 = b1 + acc[ai][bj][m][1];
;                     if (out32) { __builtin_nontemporal_store(x0, (f32x4*)(out32 + off + bj * 128)); __builtin_nontemporal_store(x1, (f32x4*)(out32 + off + bj * 128 + 4)); }
;                     else *(u32x4*)(XN + off + bj * 128) = pack8(x0, x1);
;                     ss += ((x0[0] * x0[0] + x0[1] * x0[1]) + (x0[2] * x0[2] + x0[3] * x0[3])) + ((x1[0] * x1[0] + x1[1] * x1[1]) + (x1[2] * x1[2] + x1[3] * x1[3]));
;                 }
;                 ss += __shfl_xor(ss, 16); ss += __shfl_xor(ss, 32);
;                 if (fq == 0) part[(size_t)row * 16 + u.pn * 4 + wc] = ss;
.LBB0_735:
	v_mul_f32_e32 v104, v109, v109
	v_mul_f32_e32 v95, v95, v95
	v_pk_add_f32 v[74:75], v[74:75], v[82:83]
	v_pk_add_f32 v[72:73], v[72:73], v[80:81]
	v_fmac_f32_e32 v104, v108, v108
	v_fmac_f32_e32 v95, v94, v94
	v_pk_add_f32 v[82:83], v[68:69], v[84:85]
	v_mul_f32_e32 v68, v73, v73
	v_mul_f32_e32 v69, v75, v75
	v_add_f32_e32 v94, v104, v95
	v_mul_f32_e32 v95, v97, v97
	v_pk_add_f32 v[80:81], v[70:71], v[86:87]
	v_fmac_f32_e32 v68, v72, v72
	v_fmac_f32_e32 v69, v74, v74
	v_fmac_f32_e32 v95, v96, v96
	v_mul_f32_e32 v96, v99, v99
	v_add_f32_e32 v68, v68, v69
	v_mul_f32_e32 v69, v83, v83
	v_mul_f32_e32 v70, v81, v81
	v_fmac_f32_e32 v96, v98, v98
	v_fmac_f32_e32 v69, v82, v82
	v_fmac_f32_e32 v70, v80, v80
	v_add_f32_e32 v95, v95, v96
	v_add_f32_e32 v69, v69, v70
	v_add_f32_e32 v94, v94, v95
	v_add_f32_e32 v68, v68, v69
	v_add_f32_e32 v68, v94, v68
	v_cvt_pk_bf16_f32 v70, v72, v73
	v_cvt_pk_bf16_f32 v71, v74, v75
	v_cvt_pk_bf16_f32 v72, v82, v83
	v_cvt_pk_bf16_f32 v73, v80, v81
	v_mov_b32_e32 v69, v68
	s_nop 1
	v_permlane16_swap_b32_e32 v68, v69
	v_add_f32_e32 v68, v68, v69
	v_mov_b32_e32 v69, v68
	s_nop 1
	v_permlane32_swap_b32_e32 v68, v69
	global_store_dwordx4 v[92:93], v[70:73], off offset:256
	s_and_saveexec_b64 s[30:31], s[40:41]
	s_cbranch_execz .LBB0_737
	v_lshlrev_b64 v[70:71], 6, v[226:227]
	v_lshl_add_u64 v[70:71], s[62:63], 0, v[70:71]
	v_lshl_add_u64 v[70:71], s[92:93], 2, v[70:71]
	s_lshl_b32 s58, s53, 2
	v_lshl_add_u64 v[70:71], v[70:71], 0, s[58:59]
	s_waitcnt lgkmcnt(0)
	v_add_f32_e32 v68, v68, v69
	global_store_dword v[70:71], v68, off

; __device__ __forceinline__ u32x4 pack8(f32x4 v0, f32x4 v1) { u32x4 w; w.x = pk2(v0[0], v0[1]); w.y = pk2(v0[2], v0[3]); w.z = pk2(v1[0], v1[1]); w.w = pk2(v1[2], v1[3]); return w; }
;     __device__ __forceinline__ void operator()(const f32x4 (&acc)[2][2][4][2], const Unit& u, int wr, int wc, int fr, int fq) const {
;     ...
;                 const int row = row0 + ai * 128 + m * 16; const size_t off = (size_t)row * DM + col0; float ss = 0.f;
; #pragma unroll
;                 for (int bj = 0; bj < 2; ++bj) {
;                     f32x4 b0, b1;
;                     if (base32) { b0 = __builtin_nontemporal_load((const f32x4*)(base32 + off + bj * 128)); b1 = __builtin_nontemporal_load((const f32x4*)(base32 + off + bj * 128 + 4)); }
;                     else { const u32x4 w = bw[ai][m][bj]; b0 = (f32x4){bflo(w.x), bfhi(w.x), bflo(w.y), bfhi(w.y)}; b1 = (f32x4){bflo(w.z), bfhi(w.z), bflo(w.w), bfhi(w.w)}; }
;                     const f32x4 x0 = b0 + acc[ai][bj][m][0], x1 = b1 + acc[ai][bj][m][1];
;                     if (out32) { __builtin_nontemporal_store(x0, (f32x4*)(out32 + off + bj * 128)); __builtin_nontemporal_store(x1, (f32x4*)(out32 + off + bj * 128 + 4)); }
;                     else *(u32x4*)(XN + off + bj * 128) = pack8(x0, x1);
.LBB0_740:
	v_pk_add_f32 v[70:71], v[62:63], v[70:71]
	v_pk_add_f32 v[86:87], v[60:61], v[68:69]
	v_pk_add_f32 v[74:75], v[58:59], v[74:75]
	v_pk_add_f32 v[72:73], v[56:57], v[72:73]
	v_cvt_pk_bf16_f32 v56, v86, v87
	v_cvt_pk_bf16_f32 v57, v70, v71
	v_cvt_pk_bf16_f32 v58, v72, v73
	v_cvt_pk_bf16_f32 v59, v74, v75
	v_lshl_add_u64 v[68:69], v[84:85], 1, s[54:55]
	s_and_b64 vcc, exec, s[44:45]
	global_store_dwordx4 v[68:69], v[56:59], off
	s_cbranch_vccnz .LBB0_781
	global_load_dwordx4 v[60:63], v[82:83], off offset:528 nt
	global_load_dwordx4 v[56:59], v[82:83], off offset:512 nt
	s_waitcnt vmcnt(0)
	s_cbranch_execnz .LBB0_743

; __device__ __forceinline__ u32x4 pack8(f32x4 v0, f32x4 v1) { u32x4 w; w.x = pk2(v0[0], v0[1]); w.y = pk2(v0[2], v0[3]); w.z = pk2(v1[0], v1[1]); w.w = pk2(v1[2], v1[3]); return w; }
;     __device__ __forceinline__ void operator()(const f32x4 (&acc)[2][2][4][2], const Unit& u, int wr, int wc, int fr, int fq) const {
;     ...
;                     if (base32) { b0 = __builtin_nontemporal_load((const f32x4*)(base32 + off + bj * 128)); b1 = __builtin_nontemporal_load((const f32x4*)(base32 + off + bj * 128 + 4)); }
;                     else { const u32x4 w = bw[ai][m][bj]; b0 = (f32x4){bflo(w.x), bfhi(w.x), bflo(w.y), bfhi(w.y)}; b1 = (f32x4){bflo(w.z), bfhi(w.z), bflo(w.w), bfhi(w.w)}; }
;                     const f32x4 x0 = b0 + acc[ai][bj][m][0], x1 = b1 + acc[ai][bj][m][1];
;                     if (out32) { __builtin_nontemporal_store(x0, (f32x4*)(out32 + off + bj * 128)); __builtin_nontemporal_store(x1, (f32x4*)(out32 + off + bj * 128 + 4)); }
;                     else *(u32x4*)(XN + off + bj * 128) = pack8(x0, x1);
;                     ss += ((x0[0] * x0[0] + x0[1] * x0[1]) + (x0[2] * x0[2] + x0[3] * x0[3])) + ((x1[0] * x1[0] + x1[1] * x1[1]) + (x1[2] * x1[2] + x1[3] * x1[3]));
;                 }
;                 ss += __shfl_xor(ss, 16); ss += __shfl_xor(ss, 32);
;                 if (fq == 0) part[(size_t)row * 16 + u.pn * 4 + wc] = ss;
.LBB0_743:
	v_mul_f32_e32 v82, v87, v87
	v_mul_f32_e32 v71, v71, v71
	v_pk_add_f32 v[54:55], v[54:55], v[58:59]
	v_pk_add_f32 v[52:53], v[52:53], v[56:57]
	v_fmac_f32_e32 v82, v86, v86
	v_fmac_f32_e32 v71, v70, v70
	v_pk_add_f32 v[58:59], v[48:49], v[60:61]
	v_mul_f32_e32 v48, v53, v53
	v_mul_f32_e32 v49, v55, v55
	v_add_f32_e32 v70, v82, v71
	v_mul_f32_e32 v71, v73, v73
	v_pk_add_f32 v[56:57], v[50:51], v[62:63]
	v_fmac_f32_e32 v48, v52, v52
	v_fmac_f32_e32 v49, v54, v54
	v_fmac_f32_e32 v71, v72, v72
	v_mul_f32_e32 v72, v75, v75
	v_add_f32_e32 v48, v48, v49
	v_mul_f32_e32 v49, v59, v59
	v_mul_f32_e32 v50, v57, v57
	v_fmac_f32_e32 v72, v74, v74
	v_fmac_f32_e32 v49, v58, v58
	v_fmac_f32_e32 v50, v56, v56
	v_add_f32_e32 v71, v71, v72
	v_add_f32_e32 v49, v49, v50
	v_add_f32_e32 v70, v70, v71
	v_add_f32_e32 v48, v48, v49
	v_add_f32_e32 v48, v70, v48
	v_cvt_pk_bf16_f32 v50, v52, v53
	v_cvt_pk_bf16_f32 v51, v54, v55
	v_cvt_pk_bf16_f32 v52, v58, v59
	v_cvt_pk_bf16_f32 v53, v56, v57
	v_mov_b32_e32 v49, v48
	s_nop 1
	v_permlane16_swap_b32_e32 v48, v49
	v_add_f32_e32 v48, v48, v49
	v_mov_b32_e32 v49, v48
	s_nop 1
	v_permlane32_swap_b32_e32 v48, v49
	global_store_dwordx4 v[68:69], v[50:53], off offset:256
	s_and_saveexec_b64 s[30:31], s[40:41]
	s_cbranch_execz .LBB0_745
	v_lshlrev_b64 v[50:51], 6, v[80:81]
	v_lshl_add_u64 v[50:51], s[62:63], 0, v[50:51]
	v_lshl_add_u64 v[50:51], s[92:93], 2, v[50:51]
	s_lshl_b32 s58, s53, 2
	v_lshl_add_u64 v[50:51], v[50:51], 0, s[58:59]
	s_waitcnt lgkmcnt(0)
	v_add_f32_e32 v48, v48, v49
	global_store_dword v[50:51], v48, off

; __device__ __forceinline__ u32x4 pack8(f32x4 v0, f32x4 v1) { u32x4 w; w.x = pk2(v0[0], v0[1]); w.y = pk2(v0[2], v0[3]); w.z = pk2(v1[0], v1[1]); w.w = pk2(v1[2], v1[3]); return w; }
;     __device__ __forceinline__ void operator()(const f32x4 (&acc)[2][2][4][2], const Unit& u, int wr, int wc, int fr, int fq) const {
;     ...
;                 const int row = row0 + ai * 128 + m * 16; const size_t off = (size_t)row * DM + col0; float ss = 0.f;
; #pragma unroll
;                 for (int bj = 0; bj < 2; ++bj) {
;                     f32x4 b0, b1;
;                     if (base32) { b0 = __builtin_nontemporal_load((const f32x4*)(base32 + off + bj * 128)); b1 = __builtin_nontemporal_load((const f32x4*)(base32 + off + bj * 128 + 4)); }
;                     else { const u32x4 w = bw[ai][m][bj]; b0 = (f32x4){bflo(w.x), bfhi(w.x), bflo(w.y), bfhi(w.y)}; b1 = (f32x4){bflo(w.z), bfhi(w.z), bflo(w.w), bfhi(w.w)}; }
;                     const f32x4 x0 = b0 + acc[ai][bj][m][0], x1 = b1 + acc[ai][bj][m][1];
;                     if (out32) { __builtin_nontemporal_store(x0, (f32x4*)(out32 + off + bj * 128)); __builtin_nontemporal_store(x1, (f32x4*)(out32 + off + bj * 128 + 4)); }
;                     else *(u32x4*)(XN + off + bj * 128) = pack8(x0, x1);
.LBB0_748:
	v_pk_add_f32 v[50:51], v[46:47], v[50:51]
	v_pk_add_f32 v[62:63], v[44:45], v[48:49]
	v_pk_add_f32 v[54:55], v[42:43], v[54:55]
	v_pk_add_f32 v[52:53], v[40:41], v[52:53]
	v_cvt_pk_bf16_f32 v40, v62, v63
	v_cvt_pk_bf16_f32 v41, v50, v51
	v_cvt_pk_bf16_f32 v42, v52, v53
	v_cvt_pk_bf16_f32 v43, v54, v55
	v_lshl_add_u64 v[48:49], v[60:61], 1, s[54:55]
	s_and_b64 vcc, exec, s[44:45]
	global_store_dwordx4 v[48:49], v[40:43], off
	s_cbranch_vccnz .LBB0_783
	global_load_dwordx4 v[44:47], v[58:59], off offset:528 nt
	global_load_dwordx4 v[40:43], v[58:59], off offset:512 nt
	s_waitcnt vmcnt(0)
	s_cbranch_execnz .LBB0_751

; __device__ __forceinline__ u32x4 pack8(f32x4 v0, f32x4 v1) { u32x4 w; w.x = pk2(v0[0], v0[1]); w.y = pk2(v0[2], v0[3]); w.z = pk2(v1[0], v1[1]); w.w = pk2(v1[2], v1[3]); return w; }
;     __device__ __forceinline__ void operator()(const f32x4 (&acc)[2][2][4][2], const Unit& u, int wr, int wc, int fr, int fq) const {
;     ...
;                     if (base32) { b0 = __builtin_nontemporal_load((const f32x4*)(base32 + off + bj * 128)); b1 = __builtin_nontemporal_load((const f32x4*)(base32 + off + bj * 128 + 4)); }
;                     else { const u32x4 w = bw[ai][m][bj]; b0 = (f32x4){bflo(w.x), bfhi(w.x), bflo(w.y), bfhi(w.y)}; b1 = (f32x4){bflo(w.z), bfhi(w.z), bflo(w.w), bfhi(w.w)}; }
;                     const f32x4 x0 = b0 + acc[ai][bj][m][0], x1 = b1 + acc[ai][bj][m][1];
;                     if (out32) { __builtin_nontemporal_store(x0, (f32x4*)(out32 + off + bj * 128)); __builtin_nontemporal_store(x1, (f32x4*)(out32 + off + bj * 128 + 4)); }
;                     else *(u32x4*)(XN + off + bj * 128) = pack8(x0, x1);
;                     ss += ((x0[0] * x0[0] + x0[1] * x0[1]) + (x0[2] * x0[2] + x0[3] * x0[3])) + ((x1[0] * x1[0] + x1[1] * x1[1]) + (x1[2] * x1[2] + x1[3] * x1[3]));
;                 }
;                 ss += __shfl_xor(ss, 16); ss += __shfl_xor(ss, 32);
;                 if (fq == 0) part[(size_t)row * 16 + u.pn * 4 + wc] = ss;
.LBB0_751:
	v_mul_f32_e32 v58, v63, v63
	v_mul_f32_e32 v51, v51, v51
	v_pk_add_f32 v[38:39], v[38:39], v[42:43]
	v_pk_add_f32 v[36:37], v[36:37], v[40:41]
	v_fmac_f32_e32 v58, v62, v62
	v_fmac_f32_e32 v51, v50, v50
	v_pk_add_f32 v[42:43], v[32:33], v[44:45]
	v_mul_f32_e32 v32, v37, v37
	v_mul_f32_e32 v33, v39, v39
	v_add_f32_e32 v50, v58, v51
	v_mul_f32_e32 v51, v53, v53
	v_pk_add_f32 v[40:41], v[34:35], v[46:47]
	v_fmac_f32_e32 v32, v36, v36
	v_fmac_f32_e32 v33, v38, v38
	v_fmac_f32_e32 v51, v52, v52
	v_mul_f32_e32 v52, v55, v55
	v_add_f32_e32 v32, v32, v33
	v_mul_f32_e32 v33, v43, v43
	v_mul_f32_e32 v34, v41, v41
	v_fmac_f32_e32 v52, v54, v54
	v_fmac_f32_e32 v33, v42, v42
	v_fmac_f32_e32 v34, v40, v40
	v_add_f32_e32 v51, v51, v52
	v_add_f32_e32 v33, v33, v34
	v_add_f32_e32 v50, v50, v51
	v_add_f32_e32 v32, v32, v33
	v_add_f32_e32 v32, v50, v32
	v_cvt_pk_bf16_f32 v34, v36, v37
	v_cvt_pk_bf16_f32 v35, v38, v39
	v_cvt_pk_bf16_f32 v36, v42, v43
	v_cvt_pk_bf16_f32 v37, v40, v41
	v_mov_b32_e32 v33, v32
	s_nop 1
	v_permlane16_swap_b32_e32 v32, v33
	v_add_f32_e32 v32, v32, v33
	v_mov_b32_e32 v33, v32
	s_nop 1
	v_permlane32_swap_b32_e32 v32, v33
	global_store_dwordx4 v[48:49], v[34:37], off offset:256
	s_and_saveexec_b64 s[30:31], s[40:41]
	s_cbranch_execz .LBB0_753
	v_lshlrev_b64 v[34:35], 6, v[56:57]
	v_lshl_add_u64 v[34:35], s[62:63], 0, v[34:35]
	v_lshl_add_u64 v[34:35], s[92:93], 2, v[34:35]
	s_lshl_b32 s58, s53, 2
	v_lshl_add_u64 v[34:35], v[34:35], 0, s[58:59]
	s_waitcnt lgkmcnt(0)
	v_add_f32_e32 v32, v32, v33
	global_store_dword v[34:35], v32, off

; __device__ __forceinline__ u32x4 pack8(f32x4 v0, f32x4 v1) { u32x4 w; w.x = pk2(v0[0], v0[1]); w.y = pk2(v0[2], v0[3]); w.z = pk2(v1[0], v1[1]); w.w = pk2(v1[2], v1[3]); return w; }
;     __device__ __forceinline__ void operator()(const f32x4 (&acc)[2][2][4][2], const Unit& u, int wr, int wc, int fr, int fq) const {
;     ...
;                 const int row = row0 + ai * 128 + m * 16; const size_t off = (size_t)row * DM + col0; float ss = 0.f;
; #pragma unroll
;                 for (int bj = 0; bj < 2; ++bj) {
;                     f32x4 b0, b1;
;                     if (base32) { b0 = __builtin_nontemporal_load((const f32x4*)(base32 + off + bj * 128)); b1 = __builtin_nontemporal_load((const f32x4*)(base32 + off + bj * 128 + 4)); }
;                     else { const u32x4 w = bw[ai][m][bj]; b0 = (f32x4){bflo(w.x), bfhi(w.x), bflo(w.y), bfhi(w.y)}; b1 = (f32x4){bflo(w.z), bfhi(w.z), bflo(w.w), bfhi(w.w)}; }
;                     const f32x4 x0 = b0 + acc[ai][bj][m][0], x1 = b1 + acc[ai][bj][m][1];
;                     if (out32) { __builtin_nontemporal_store(x0, (f32x4*)(out32 + off + bj * 128)); __builtin_nontemporal_store(x1, (f32x4*)(out32 + off + bj * 128 + 4)); }
;                     else *(u32x4*)(XN + off + bj * 128) = pack8(x0, x1);
.LBB0_756:
	v_pk_add_f32 v[34:35], v[30:31], v[34:35]
	v_pk_add_f32 v[46:47], v[28:29], v[32:33]
	v_pk_add_f32 v[38:39], v[26:27], v[38:39]
	v_pk_add_f32 v[36:37], v[24:25], v[36:37]
	v_cvt_pk_bf16_f32 v24, v46, v47
	v_cvt_pk_bf16_f32 v25, v34, v35
	v_cvt_pk_bf16_f32 v26, v36, v37
	v_cvt_pk_bf16_f32 v27, v38, v39
	v_lshl_add_u64 v[32:33], v[44:45], 1, s[54:55]
	s_and_b64 vcc, exec, s[44:45]
	global_store_dwordx4 v[32:33], v[24:27], off
	s_cbranch_vccnz .LBB0_785
	global_load_dwordx4 v[28:31], v[42:43], off offset:528 nt
	global_load_dwordx4 v[24:27], v[42:43], off offset:512 nt
	s_waitcnt vmcnt(0)
	s_cbranch_execnz .LBB0_759

; __device__ __forceinline__ u32x4 pack8(f32x4 v0, f32x4 v1) { u32x4 w; w.x = pk2(v0[0], v0[1]); w.y = pk2(v0[2], v0[3]); w.z = pk2(v1[0], v1[1]); w.w = pk2(v1[2], v1[3]); return w; }
;     __device__ __forceinline__ void operator()(const f32x4 (&acc)[2][2][4][2], const Unit& u, int wr, int wc, int fr, int fq) const {
;     ...
;                     if (base32) { b0 = __builtin_nontemporal_load((const f32x4*)(base32 + off + bj * 128)); b1 = __builtin_nontemporal_load((const f32x4*)(base32 + off + bj * 128 + 4)); }
;                     else { const u32x4 w = bw[ai][m][bj]; b0 = (f32x4){bflo(w.x), bfhi(w.x), bflo(w.y), bfhi(w.y)}; b1 = (f32x4){bflo(w.z), bfhi(w.z), bflo(w.w), bfhi(w.w)}; }
;                     const f32x4 x0 = b0 + acc[ai][bj][m][0], x1 = b1 + acc[ai][bj][m][1];
;                     if (out32) { __builtin_nontemporal_store(x0, (f32x4*)(out32 + off + bj * 128)); __builtin_nontemporal_store(x1, (f32x4*)(out32 + off + bj * 128 + 4)); }
;                     else *(u32x4*)(XN + off + bj * 128) = pack8(x0, x1);
;                     ss += ((x0[0] * x0[0] + x0[1] * x0[1]) + (x0[2] * x0[2] + x0[3] * x0[3])) + ((x1[0] * x1[0] + x1[1] * x1[1]) + (x1[2] * x1[2] + x1[3] * x1[3]));
;                 }
;                 ss += __shfl_xor(ss, 16); ss += __shfl_xor(ss, 32);
;                 if (fq == 0) part[(size_t)row * 16 + u.pn * 4 + wc] = ss;
.LBB0_759:
	v_mul_f32_e32 v42, v47, v47
	v_mul_f32_e32 v35, v35, v35
	v_pk_add_f32 v[22:23], v[22:23], v[26:27]
	v_pk_add_f32 v[20:21], v[20:21], v[24:25]
	v_fmac_f32_e32 v42, v46, v46
	v_fmac_f32_e32 v35, v34, v34
	v_pk_add_f32 v[26:27], v[16:17], v[28:29]
	v_mul_f32_e32 v16, v21, v21
	v_mul_f32_e32 v17, v23, v23
	v_add_f32_e32 v34, v42, v35
	v_mul_f32_e32 v35, v37, v37
	v_pk_add_f32 v[24:25], v[18:19], v[30:31]
	v_fmac_f32_e32 v16, v20, v20
	v_fmac_f32_e32 v17, v22, v22
	v_fmac_f32_e32 v35, v36, v36
	v_mul_f32_e32 v36, v39, v39
	v_add_f32_e32 v16, v16, v17
	v_mul_f32_e32 v17, v27, v27
	v_mul_f32_e32 v18, v25, v25
	v_fmac_f32_e32 v36, v38, v38
	v_fmac_f32_e32 v17, v26, v26
	v_fmac_f32_e32 v18, v24, v24
	v_add_f32_e32 v35, v35, v36
	v_add_f32_e32 v17, v17, v18
	v_add_f32_e32 v34, v34, v35
	v_add_f32_e32 v16, v16, v17
	v_add_f32_e32 v16, v34, v16
	v_cvt_pk_bf16_f32 v18, v20, v21
	v_cvt_pk_bf16_f32 v19, v22, v23
	v_cvt_pk_bf16_f32 v20, v26, v27
	v_cvt_pk_bf16_f32 v21, v24, v25
	v_mov_b32_e32 v17, v16
	s_nop 1
	v_permlane16_swap_b32_e32 v16, v17
	v_add_f32_e32 v16, v16, v17
	v_mov_b32_e32 v17, v16
	s_nop 1
	v_permlane32_swap_b32_e32 v16, v17
	global_store_dwordx4 v[32:33], v[18:21], off offset:256
	s_and_saveexec_b64 s[30:31], s[40:41]
	s_cbranch_execz .LBB0_761
	v_lshlrev_b64 v[18:19], 6, v[40:41]
	v_lshl_add_u64 v[18:19], s[62:63], 0, v[18:19]
	v_lshl_add_u64 v[18:19], s[92:93], 2, v[18:19]
	s_lshl_b32 s58, s53, 2
	v_lshl_add_u64 v[18:19], v[18:19], 0, s[58:59]
	s_waitcnt lgkmcnt(0)
	v_add_f32_e32 v16, v16, v17
	global_store_dword v[18:19], v16, off

; __device__ __forceinline__ u32x4 pack8(f32x4 v0, f32x4 v1) { u32x4 w; w.x = pk2(v0[0], v0[1]); w.y = pk2(v0[2], v0[3]); w.z = pk2(v1[0], v1[1]); w.w = pk2(v1[2], v1[3]); return w; }
;     __device__ __forceinline__ void operator()(const f32x4 (&acc)[2][2][4][2], const Unit& u, int wr, int wc, int fr, int fq) const {
;     ...
;                 const int row = row0 + ai * 128 + m * 16; const size_t off = (size_t)row * DM + col0; float ss = 0.f;
; #pragma unroll
;                 for (int bj = 0; bj < 2; ++bj) {
;                     f32x4 b0, b1;
;                     if (base32) { b0 = __builtin_nontemporal_load((const f32x4*)(base32 + off + bj * 128)); b1 = __builtin_nontemporal_load((const f32x4*)(base32 + off + bj * 128 + 4)); }
;                     else { const u32x4 w = bw[ai][m][bj]; b0 = (f32x4){bflo(w.x), bfhi(w.x), bflo(w.y), bfhi(w.y)}; b1 = (f32x4){bflo(w.z), bfhi(w.z), bflo(w.w), bfhi(w.w)}; }
;                     const f32x4 x0 = b0 + acc[ai][bj][m][0], x1 = b1 + acc[ai][bj][m][1];
;                     if (out32) { __builtin_nontemporal_store(x0, (f32x4*)(out32 + off + bj * 128)); __builtin_nontemporal_store(x1, (f32x4*)(out32 + off + bj * 128 + 4)); }
;                     else *(u32x4*)(XN + off + bj * 128) = pack8(x0, x1);
.LBB0_764:
	v_pk_add_f32 v[18:19], v[14:15], v[18:19]
	v_pk_add_f32 v[30:31], v[12:13], v[16:17]
	v_pk_add_f32 v[22:23], v[10:11], v[22:23]
	v_pk_add_f32 v[20:21], v[8:9], v[20:21]
	v_cvt_pk_bf16_f32 v8, v30, v31
	v_cvt_pk_bf16_f32 v9, v18, v19
	v_cvt_pk_bf16_f32 v10, v20, v21
	v_cvt_pk_bf16_f32 v11, v22, v23
	v_lshl_add_u64 v[16:17], v[28:29], 1, s[54:55]
	s_and_b64 vcc, exec, s[44:45]
	global_store_dwordx4 v[16:17], v[8:11], off
	s_cbranch_vccnz .LBB0_787
	global_load_dwordx4 v[12:15], v[26:27], off offset:528 nt
	global_load_dwordx4 v[8:11], v[26:27], off offset:512 nt
	s_waitcnt vmcnt(0)
	s_cbranch_execnz .LBB0_767

; __device__ __forceinline__ u32x4 pack8(f32x4 v0, f32x4 v1) { u32x4 w; w.x = pk2(v0[0], v0[1]); w.y = pk2(v0[2], v0[3]); w.z = pk2(v1[0], v1[1]); w.w = pk2(v1[2], v1[3]); return w; }
;     __device__ __forceinline__ void operator()(const f32x4 (&acc)[2][2][4][2], const Unit& u, int wr, int wc, int fr, int fq) const {
;     ...
;                     if (base32) { b0 = __builtin_nontemporal_load((const f32x4*)(base32 + off + bj * 128)); b1 = __builtin_nontemporal_load((const f32x4*)(base32 + off + bj * 128 + 4)); }
;                     else { const u32x4 w = bw[ai][m][bj]; b0 = (f32x4){bflo(w.x), bfhi(w.x), bflo(w.y), bfhi(w.y)}; b1 = (f32x4){bflo(w.z), bfhi(w.z), bflo(w.w), bfhi(w.w)}; }
;                     const f32x4 x0 = b0 + acc[ai][bj][m][0], x1 = b1 + acc[ai][bj][m][1];
;                     if (out32) { __builtin_nontemporal_store(x0, (f32x4*)(out32 + off + bj * 128)); __builtin_nontemporal_store(x1, (f32x4*)(out32 + off + bj * 128 + 4)); }
;                     else *(u32x4*)(XN + off + bj * 128) = pack8(x0, x1);
;                     ss += ((x0[0] * x0[0] + x0[1] * x0[1]) + (x0[2] * x0[2] + x0[3] * x0[3])) + ((x1[0] * x1[0] + x1[1] * x1[1]) + (x1[2] * x1[2] + x1[3] * x1[3]));
;                 }
;                 ss += __shfl_xor(ss, 16); ss += __shfl_xor(ss, 32);
;                 if (fq == 0) part[(size_t)row * 16 + u.pn * 4 + wc] = ss;
.LBB0_767:
	v_mul_f32_e32 v26, v31, v31
	v_mul_f32_e32 v19, v19, v19
	v_pk_add_f32 v[6:7], v[6:7], v[10:11]
	v_pk_add_f32 v[4:5], v[4:5], v[8:9]
	v_fmac_f32_e32 v26, v30, v30
	v_fmac_f32_e32 v19, v18, v18
	v_pk_add_f32 v[10:11], v[0:1], v[12:13]
	v_mul_f32_e32 v0, v5, v5
	v_mul_f32_e32 v1, v7, v7
	v_add_f32_e32 v18, v26, v19
	v_mul_f32_e32 v19, v21, v21
	v_pk_add_f32 v[8:9], v[2:3], v[14:15]
	v_fmac_f32_e32 v0, v4, v4
	v_fmac_f32_e32 v1, v6, v6
	v_fmac_f32_e32 v19, v20, v20
	v_mul_f32_e32 v20, v23, v23
	v_add_f32_e32 v0, v0, v1
	v_mul_f32_e32 v1, v11, v11
	v_mul_f32_e32 v2, v9, v9
	v_fmac_f32_e32 v20, v22, v22
	v_fmac_f32_e32 v1, v10, v10
	v_fmac_f32_e32 v2, v8, v8
	v_add_f32_e32 v19, v19, v20
	v_add_f32_e32 v1, v1, v2
	v_add_f32_e32 v18, v18, v19
	v_add_f32_e32 v0, v0, v1
	v_add_f32_e32 v0, v18, v0
	v_cvt_pk_bf16_f32 v2, v4, v5
	v_cvt_pk_bf16_f32 v3, v6, v7
	v_cvt_pk_bf16_f32 v4, v10, v11
	v_cvt_pk_bf16_f32 v5, v8, v9
	v_mov_b32_e32 v1, v0
	s_nop 1
	v_permlane16_swap_b32_e32 v0, v1
	v_add_f32_e32 v0, v0, v1
	v_mov_b32_e32 v1, v0
	s_nop 1
	v_permlane32_swap_b32_e32 v0, v1
	global_store_dwordx4 v[16:17], v[2:5], off offset:256
	s_and_saveexec_b64 s[30:31], s[40:41]
	s_cbranch_execz .LBB0_769
	v_lshlrev_b64 v[2:3], 6, v[24:25]
	v_lshl_add_u64 v[2:3], s[62:63], 0, v[2:3]
	v_lshl_add_u64 v[2:3], s[92:93], 2, v[2:3]
	s_lshl_b32 s58, s53, 2
	v_lshl_add_u64 v[2:3], v[2:3], 0, s[58:59]
	s_waitcnt lgkmcnt(0)
	v_add_f32_e32 v0, v0, v1
	global_store_dword v[2:3], v0, off

; __device__ __forceinline__ u32x4 pack8(f32x4 v0, f32x4 v1) { u32x4 w; w.x = pk2(v0[0], v0[1]); w.y = pk2(v0[2], v0[3]); w.z = pk2(v1[0], v1[1]); w.w = pk2(v1[2], v1[3]); return w; }
;     __device__ __forceinline__ void operator()(const f32x4 (&acc)[2][2][4][2], const Unit& u, int wr, int wc, int fr, int fq) const {
;     ...
;         if (!base32) {
; #pragma unroll
;             for (int ai = 0; ai < 2; ++ai)
; #pragma unroll
;                 for (int m = 0; m < 4; ++m)
; #pragma unroll
;                     for (int bj = 0; bj < 2; ++bj) bw[ai][m][bj] = *(const u32x4*)(XN + (size_t)(row0 + ai * 128 + m * 16) * DM + col0 + bj * 128);
;         }
; #pragma unroll
;         for (int ai = 0; ai < 2; ++ai)
; #pragma unroll
;             for (int m = 0; m < 4; ++m) {
;                 const int row = row0 + ai * 128 + m * 16; const size_t off = (size_t)row * DM + col0; float ss = 0.f;
; #pragma unroll
;                 for (int bj = 0; bj < 2; ++bj) {
;                     f32x4 b0, b1;
;                     if (base32) { b0 = __builtin_nontemporal_load((const f32x4*)(base32 + off + bj * 128)); b1 = __builtin_nontemporal_load((const f32x4*)(base32 + off + bj * 128 + 4)); }
;                     else { const u32x4 w = bw[ai][m][bj]; b0 = (f32x4){bflo(w.x), bfhi(w.x), bflo(w.y), bfhi(w.y)}; b1 = (f32x4){bflo(w.z), bfhi(w.z), bflo(w.w), bfhi(w.w)}; }
;                     const f32x4 x0 = b0 + acc[ai][bj][m][0], x1 = b1 + acc[ai][bj][m][1];
;                     if (out32) { __builtin_nontemporal_store(x0, (f32x4*)(out32 + off + bj * 128)); __builtin_nontemporal_store(x1, (f32x4*)(out32 + off + bj * 128 + 4)); }
;                     else *(u32x4*)(XN + off + bj * 128) = pack8(x0, x1);
.LBB0_939:
	v_lshl_add_u32 v228, s42, 8, v234
	v_lshl_or_b32 v214, s22, 8, v244
	v_ashrrev_i32_e32 v215, 31, v214
	v_ashrrev_i32_e32 v229, 31, v228
	v_lshl_add_u64 v[212:213], v[214:215], 1, s[54:55]
	v_lshlrev_b64 v[80:81], 11, v[228:229]
	v_or_b32_e32 v226, 16, v228
	v_lshl_add_u64 v[80:81], v[212:213], 0, v[80:81]
	v_ashrrev_i32_e32 v227, 31, v226
	global_load_dwordx4 v[246:249], v[80:81], off
	global_load_dwordx4 v[184:187], v[80:81], off offset:256
	v_lshlrev_b64 v[80:81], 11, v[226:227]
	v_or_b32_e32 v224, 32, v228
	v_lshl_add_u64 v[80:81], v[212:213], 0, v[80:81]
	v_ashrrev_i32_e32 v225, 31, v224
	global_load_dwordx4 v[180:183], v[80:81], off
	global_load_dwordx4 v[176:179], v[80:81], off offset:256
	v_lshlrev_b64 v[80:81], 11, v[224:225]
	v_or_b32_e32 v222, 48, v228
	v_lshl_add_u64 v[80:81], v[212:213], 0, v[80:81]
	v_ashrrev_i32_e32 v223, 31, v222
	global_load_dwordx4 v[172:175], v[80:81], off
	global_load_dwordx4 v[168:171], v[80:81], off offset:256
	v_lshlrev_b64 v[80:81], 11, v[222:223]
	v_add_u32_e32 v220, 0x80, v228
	v_lshl_add_u64 v[80:81], v[212:213], 0, v[80:81]
	v_ashrrev_i32_e32 v221, 31, v220
	global_load_dwordx4 v[164:167], v[80:81], off
	global_load_dwordx4 v[160:163], v[80:81], off offset:256
	v_lshlrev_b64 v[80:81], 11, v[220:221]
	v_add_u32_e32 v218, 0x90, v228
	v_lshl_add_u64 v[80:81], v[212:213], 0, v[80:81]
	v_ashrrev_i32_e32 v219, 31, v218
	global_load_dwordx4 v[156:159], v[80:81], off
	global_load_dwordx4 v[144:147], v[80:81], off offset:256
	v_lshlrev_b64 v[80:81], 11, v[218:219]
	v_add_u32_e32 v216, 0xa0, v228
	v_lshl_add_u64 v[80:81], v[212:213], 0, v[80:81]
	v_ashrrev_i32_e32 v217, 31, v216
	global_load_dwordx4 v[132:135], v[80:81], off
	global_load_dwordx4 v[124:127], v[80:81], off offset:256
	v_lshlrev_b64 v[80:81], 11, v[216:217]
	v_add_u32_e32 v198, 0xb0, v228
	v_lshl_add_u64 v[80:81], v[212:213], 0, v[80:81]
	v_ashrrev_i32_e32 v199, 31, v198
	global_load_dwordx4 v[112:115], v[80:81], off
	global_load_dwordx4 v[104:107], v[80:81], off offset:256
	v_lshlrev_b64 v[80:81], 11, v[198:199]
	v_lshl_add_u64 v[80:81], v[212:213], 0, v[80:81]
	global_load_dwordx4 v[88:91], v[80:81], off
	s_nop 0
	global_load_dwordx4 v[80:83], v[80:81], off offset:256
	v_cndmask_b32_e64 v230, 0, 1, s[16:17]
	v_cmp_ne_u32_e64 s[42:43], 1, v230
	v_lshlrev_b64 v[230:231], 10, v[228:229]
	v_lshl_add_u64 v[232:233], v[230:231], 0, v[214:215]
	s_andn2_b64 vcc, exec, s[16:17]
	v_lshl_add_u64 v[232:233], v[232:233], 2, s[10:11]
	s_waitcnt vmcnt(0) lgkmcnt(0)
	v_lshlrev_b32_e32 v250, 16, v246
	v_and_b32_e32 v251, 0xffff0000, v246
	v_lshlrev_b32_e32 v246, 16, v247
	v_and_b32_e32 v247, 0xffff0000, v247
	v_lshlrev_b32_e32 v240, 16, v248
	v_and_b32_e32 v241, 0xffff0000, v248
	v_lshlrev_b32_e32 v248, 16, v249
	v_and_b32_e32 v249, 0xffff0000, v249
	v_pk_add_f32 v[154:155], v[154:155], v[246:247]
	v_pk_add_f32 v[152:153], v[152:153], v[250:251]
	v_pk_add_f32 v[150:151], v[150:151], v[248:249]
	v_pk_add_f32 v[148:149], v[148:149], v[240:241]
	s_cbranch_vccnz .LBB0_1006
	global_store_dwordx4 v[232:233], v[152:155], off nt
	global_store_dwordx4 v[232:233], v[148:151], off offset:16 nt
	v_lshl_add_u64 v[230:231], v[230:231], 1, v[212:213]
	s_movk_i32 s87, 0x80
	s_cbranch_execnz .LBB0_942
.LBB0_941:
	v_cvt_pk_bf16_f32 v246, v152, v153
	v_cvt_pk_bf16_f32 v247, v154, v155
	v_cvt_pk_bf16_f32 v248, v148, v149
	v_cvt_pk_bf16_f32 v249, v150, v151
	global_store_dwordx4 v[230:231], v[246:249], off

; __device__ __forceinline__ u32x4 pack8(f32x4 v0, f32x4 v1) { u32x4 w; w.x = pk2(v0[0], v0[1]); w.y = pk2(v0[2], v0[3]); w.z = pk2(v1[0], v1[1]); w.w = pk2(v1[2], v1[3]); return w; }
;     __device__ __forceinline__ void operator()(const f32x4 (&acc)[2][2][4][2], const Unit& u, int wr, int wc, int fr, int fq) const {
;     ...
;                     else *(u32x4*)(XN + off + bj * 128) = pack8(x0, x1);
;                     ss += ((x0[0] * x0[0] + x0[1] * x0[1]) + (x0[2] * x0[2] + x0[3] * x0[3])) + ((x1[0] * x1[0] + x1[1] * x1[1]) + (x1[2] * x1[2] + x1[3] * x1[3]));
;                 }
;                 ss += __shfl_xor(ss, 16); ss += __shfl_xor(ss, 32);
;                 if (fq == 0) part[(size_t)row * 16 + u.pn * 4 + wc] = ss;
.LBB0_944:
	v_cvt_pk_bf16_f32 v184, v140, v141
	v_cvt_pk_bf16_f32 v185, v142, v143
	v_cvt_pk_bf16_f32 v186, v136, v137
	v_cvt_pk_bf16_f32 v187, v138, v139
	global_store_dwordx4 v[230:231], v[184:187], off offset:256
.LBB0_945:
	v_mul_f32_e32 v153, v153, v153
	v_mul_f32_e32 v149, v149, v149
	v_fmac_f32_e32 v153, v152, v152
	v_mul_f32_e32 v152, v155, v155
	v_fmac_f32_e32 v149, v148, v148
	v_mul_f32_e32 v148, v151, v151
	v_fmac_f32_e32 v152, v154, v154
	v_fmac_f32_e32 v148, v150, v150
	v_mul_f32_e32 v141, v141, v141
	v_mul_f32_e32 v137, v137, v137
	v_add_f32_e32 v152, v153, v152
	v_add_f32_e32 v148, v149, v148
	v_and_b32_e32 v150, 64, v243
	v_fmac_f32_e32 v141, v140, v140
	v_mul_f32_e32 v140, v143, v143
	v_fmac_f32_e32 v137, v136, v136
	v_mul_f32_e32 v136, v139, v139
	v_add_f32_e32 v149, v152, v148
	v_xor_b32_e32 v148, 16, v243
	v_add_u32_e32 v150, 64, v150
	v_fmac_f32_e32 v140, v142, v142
	v_fmac_f32_e32 v136, v138, v138
	v_cmp_lt_i32_e32 vcc, v148, v150
	v_add_f32_e32 v140, v141, v140
	v_add_f32_e32 v136, v137, v136
	v_cndmask_b32_e32 v148, v243, v148, vcc
	v_add_f32_e32 v136, v140, v136
	v_lshlrev_b32_e32 v148, 2, v148
	v_add_f32_e32 v136, v149, v136
	v_xor_b32_e32 v138, 32, v243
	v_cmp_lt_i32_e32 vcc, v138, v150
	s_lshl_b32 s22, s22, 2
	s_ashr_i32 s23, s22, 31
	v_cndmask_b32_e32 v138, v243, v138, vcc
	v_lshlrev_b32_e32 v140, 2, v138
	v_mov_b32_e32 v137, v136
	s_nop 1
	v_permlane16_swap_b32_e32 v136, v137
	v_add_f32_e32 v136, v136, v137
	v_mov_b32_e32 v137, v136
	s_nop 1
	v_permlane32_swap_b32_e32 v136, v137
	s_and_saveexec_b64 s[44:45], s[38:39]
	s_cbranch_execz .LBB0_947
	v_lshlrev_b64 v[138:139], 6, v[228:229]
	v_lshl_add_u64 v[138:139], s[62:63], 0, v[138:139]
	v_lshl_add_u64 v[138:139], s[22:23], 2, v[138:139]
	s_lshl_b32 s58, s53, 2
	v_lshl_add_u64 v[138:139], v[138:139], 0, s[58:59]
	s_waitcnt lgkmcnt(0)
	v_add_f32_e32 v136, v136, v137
	global_store_dword v[138:139], v136, off

; __device__ __forceinline__ u32x4 pack8(f32x4 v0, f32x4 v1) { u32x4 w; w.x = pk2(v0[0], v0[1]); w.y = pk2(v0[2], v0[3]); w.z = pk2(v1[0], v1[1]); w.w = pk2(v1[2], v1[3]); return w; }
;     __device__ __forceinline__ void operator()(const f32x4 (&acc)[2][2][4][2], const Unit& u, int wr, int wc, int fr, int fq) const {
;     ...
;                 const int row = row0 + ai * 128 + m * 16; const size_t off = (size_t)row * DM + col0; float ss = 0.f;
; #pragma unroll
;                 for (int bj = 0; bj < 2; ++bj) {
;                     f32x4 b0, b1;
;                     if (base32) { b0 = __builtin_nontemporal_load((const f32x4*)(base32 + off + bj * 128)); b1 = __builtin_nontemporal_load((const f32x4*)(base32 + off + bj * 128 + 4)); }
;                     else { const u32x4 w = bw[ai][m][bj]; b0 = (f32x4){bflo(w.x), bfhi(w.x), bflo(w.y), bfhi(w.y)}; b1 = (f32x4){bflo(w.z), bfhi(w.z), bflo(w.w), bfhi(w.w)}; }
;                     const f32x4 x0 = b0 + acc[ai][bj][m][0], x1 = b1 + acc[ai][bj][m][1];
;                     if (out32) { __builtin_nontemporal_store(x0, (f32x4*)(out32 + off + bj * 128)); __builtin_nontemporal_store(x1, (f32x4*)(out32 + off + bj * 128 + 4)); }
;                     else *(u32x4*)(XN + off + bj * 128) = pack8(x0, x1);
.LBB0_949:
	v_cvt_pk_bf16_f32 v150, v128, v129
	v_cvt_pk_bf16_f32 v151, v130, v131
	v_cvt_pk_bf16_f32 v152, v120, v121
	v_cvt_pk_bf16_f32 v153, v122, v123
	global_store_dwordx4 v[136:137], v[150:153], off

; __device__ __forceinline__ u32x4 pack8(f32x4 v0, f32x4 v1) { u32x4 w; w.x = pk2(v0[0], v0[1]); w.y = pk2(v0[2], v0[3]); w.z = pk2(v1[0], v1[1]); w.w = pk2(v1[2], v1[3]); return w; }
;     __device__ __forceinline__ void operator()(const f32x4 (&acc)[2][2][4][2], const Unit& u, int wr, int wc, int fr, int fq) const {
;     ...
;                     else *(u32x4*)(XN + off + bj * 128) = pack8(x0, x1);
;                     ss += ((x0[0] * x0[0] + x0[1] * x0[1]) + (x0[2] * x0[2] + x0[3] * x0[3])) + ((x1[0] * x1[0] + x1[1] * x1[1]) + (x1[2] * x1[2] + x1[3] * x1[3]));
;                 }
;                 ss += __shfl_xor(ss, 16); ss += __shfl_xor(ss, 32);
;                 if (fq == 0) part[(size_t)row * 16 + u.pn * 4 + wc] = ss;
.LBB0_952:
	v_cvt_pk_bf16_f32 v150, v116, v117
	v_cvt_pk_bf16_f32 v151, v118, v119
	v_cvt_pk_bf16_f32 v152, v108, v109
	v_cvt_pk_bf16_f32 v153, v110, v111
	global_store_dwordx4 v[136:137], v[150:153], off offset:256
.LBB0_953:
	v_mul_f32_e32 v129, v129, v129
	v_mul_f32_e32 v121, v121, v121
	v_mul_f32_e32 v117, v117, v117
	v_mul_f32_e32 v109, v109, v109
	v_fmac_f32_e32 v129, v128, v128
	v_mul_f32_e32 v128, v131, v131
	v_fmac_f32_e32 v121, v120, v120
	v_mul_f32_e32 v120, v123, v123
	v_fmac_f32_e32 v117, v116, v116
	v_mul_f32_e32 v116, v119, v119
	v_fmac_f32_e32 v109, v108, v108
	v_mul_f32_e32 v108, v111, v111
	v_fmac_f32_e32 v128, v130, v130
	v_fmac_f32_e32 v120, v122, v122
	v_fmac_f32_e32 v116, v118, v118
	v_fmac_f32_e32 v108, v110, v110
	v_add_f32_e32 v128, v129, v128
	v_add_f32_e32 v120, v121, v120
	v_add_f32_e32 v116, v117, v116
	v_add_f32_e32 v108, v109, v108
	v_add_f32_e32 v120, v128, v120
	v_add_f32_e32 v108, v116, v108
	v_add_f32_e32 v108, v120, v108
	v_mov_b32_e32 v109, v108
	s_nop 1
	v_permlane16_swap_b32_e32 v108, v109
	v_add_f32_e32 v108, v108, v109
	v_mov_b32_e32 v109, v108
	s_nop 1
	v_permlane32_swap_b32_e32 v108, v109
	s_and_saveexec_b64 s[44:45], s[38:39]
	s_cbranch_execz .LBB0_955
	v_lshlrev_b64 v[110:111], 6, v[226:227]
	v_lshl_add_u64 v[110:111], s[62:63], 0, v[110:111]
	v_lshl_add_u64 v[110:111], s[22:23], 2, v[110:111]
	s_lshl_b32 s58, s53, 2
	v_lshl_add_u64 v[110:111], v[110:111], 0, s[58:59]
	s_waitcnt lgkmcnt(0)
	v_add_f32_e32 v108, v108, v109
	global_store_dword v[110:111], v108, off

; __device__ __forceinline__ u32x4 pack8(f32x4 v0, f32x4 v1) { u32x4 w; w.x = pk2(v0[0], v0[1]); w.y = pk2(v0[2], v0[3]); w.z = pk2(v1[0], v1[1]); w.w = pk2(v1[2], v1[3]); return w; }
;     __device__ __forceinline__ void operator()(const f32x4 (&acc)[2][2][4][2], const Unit& u, int wr, int wc, int fr, int fq) const {
;     ...
;                 const int row = row0 + ai * 128 + m * 16; const size_t off = (size_t)row * DM + col0; float ss = 0.f;
; #pragma unroll
;                 for (int bj = 0; bj < 2; ++bj) {
;                     f32x4 b0, b1;
;                     if (base32) { b0 = __builtin_nontemporal_load((const f32x4*)(base32 + off + bj * 128)); b1 = __builtin_nontemporal_load((const f32x4*)(base32 + off + bj * 128 + 4)); }
;                     else { const u32x4 w = bw[ai][m][bj]; b0 = (f32x4){bflo(w.x), bfhi(w.x), bflo(w.y), bfhi(w.y)}; b1 = (f32x4){bflo(w.z), bfhi(w.z), bflo(w.w), bfhi(w.w)}; }
;                     const f32x4 x0 = b0 + acc[ai][bj][m][0], x1 = b1 + acc[ai][bj][m][1];
;                     if (out32) { __builtin_nontemporal_store(x0, (f32x4*)(out32 + off + bj * 128)); __builtin_nontemporal_store(x1, (f32x4*)(out32 + off + bj * 128 + 4)); }
;                     else *(u32x4*)(XN + off + bj * 128) = pack8(x0, x1);
.LBB0_957:
	v_cvt_pk_bf16_f32 v116, v100, v101
	v_cvt_pk_bf16_f32 v117, v102, v103
	v_cvt_pk_bf16_f32 v118, v96, v97
	v_cvt_pk_bf16_f32 v119, v98, v99
	global_store_dwordx4 v[108:109], v[116:119], off

; __device__ __forceinline__ u32x4 pack8(f32x4 v0, f32x4 v1) { u32x4 w; w.x = pk2(v0[0], v0[1]); w.y = pk2(v0[2], v0[3]); w.z = pk2(v1[0], v1[1]); w.w = pk2(v1[2], v1[3]); return w; }
;     __device__ __forceinline__ void operator()(const f32x4 (&acc)[2][2][4][2], const Unit& u, int wr, int wc, int fr, int fq) const {
;     ...
;                     else *(u32x4*)(XN + off + bj * 128) = pack8(x0, x1);
;                     ss += ((x0[0] * x0[0] + x0[1] * x0[1]) + (x0[2] * x0[2] + x0[3] * x0[3])) + ((x1[0] * x1[0] + x1[1] * x1[1]) + (x1[2] * x1[2] + x1[3] * x1[3]));
;                 }
;                 ss += __shfl_xor(ss, 16); ss += __shfl_xor(ss, 32);
;                 if (fq == 0) part[(size_t)row * 16 + u.pn * 4 + wc] = ss;
.LBB0_960:
	v_cvt_pk_bf16_f32 v116, v92, v93
	v_cvt_pk_bf16_f32 v117, v94, v95
	v_cvt_pk_bf16_f32 v118, v84, v85
	v_cvt_pk_bf16_f32 v119, v86, v87
	global_store_dwordx4 v[108:109], v[116:119], off offset:256
.LBB0_961:
	v_mul_f32_e32 v101, v101, v101
	v_mul_f32_e32 v97, v97, v97
	v_mul_f32_e32 v93, v93, v93
	v_mul_f32_e32 v85, v85, v85
	v_fmac_f32_e32 v101, v100, v100
	v_mul_f32_e32 v100, v103, v103
	v_fmac_f32_e32 v97, v96, v96
	v_mul_f32_e32 v96, v99, v99
	v_fmac_f32_e32 v93, v92, v92
	v_mul_f32_e32 v92, v95, v95
	v_fmac_f32_e32 v85, v84, v84
	v_mul_f32_e32 v84, v87, v87
	v_fmac_f32_e32 v100, v102, v102
	v_fmac_f32_e32 v96, v98, v98
	v_fmac_f32_e32 v92, v94, v94
	v_fmac_f32_e32 v84, v86, v86
	v_add_f32_e32 v100, v101, v100
	v_add_f32_e32 v96, v97, v96
	v_add_f32_e32 v92, v93, v92
	v_add_f32_e32 v84, v85, v84
	v_add_f32_e32 v96, v100, v96
	v_add_f32_e32 v84, v92, v84
	v_add_f32_e32 v84, v96, v84
	v_mov_b32_e32 v85, v84
	s_nop 1
	v_permlane16_swap_b32_e32 v84, v85
	v_add_f32_e32 v84, v84, v85
	v_mov_b32_e32 v85, v84
	s_nop 1
	v_permlane32_swap_b32_e32 v84, v85
	s_and_saveexec_b64 s[44:45], s[38:39]
	s_cbranch_execz .LBB0_963
	v_lshlrev_b64 v[86:87], 6, v[224:225]
	v_lshl_add_u64 v[86:87], s[62:63], 0, v[86:87]
	v_lshl_add_u64 v[86:87], s[22:23], 2, v[86:87]
	s_lshl_b32 s58, s53, 2
	v_lshl_add_u64 v[86:87], v[86:87], 0, s[58:59]
	s_waitcnt lgkmcnt(0)
	v_add_f32_e32 v84, v84, v85
	global_store_dword v[86:87], v84, off

; __device__ __forceinline__ u32x4 pack8(f32x4 v0, f32x4 v1) { u32x4 w; w.x = pk2(v0[0], v0[1]); w.y = pk2(v0[2], v0[3]); w.z = pk2(v1[0], v1[1]); w.w = pk2(v1[2], v1[3]); return w; }
;     __device__ __forceinline__ void operator()(const f32x4 (&acc)[2][2][4][2], const Unit& u, int wr, int wc, int fr, int fq) const {
;     ...
;                 const int row = row0 + ai * 128 + m * 16; const size_t off = (size_t)row * DM + col0; float ss = 0.f;
; #pragma unroll
;                 for (int bj = 0; bj < 2; ++bj) {
;                     f32x4 b0, b1;
;                     if (base32) { b0 = __builtin_nontemporal_load((const f32x4*)(base32 + off + bj * 128)); b1 = __builtin_nontemporal_load((const f32x4*)(base32 + off + bj * 128 + 4)); }
;                     else { const u32x4 w = bw[ai][m][bj]; b0 = (f32x4){bflo(w.x), bfhi(w.x), bflo(w.y), bfhi(w.y)}; b1 = (f32x4){bflo(w.z), bfhi(w.z), bflo(w.w), bfhi(w.w)}; }
;                     const f32x4 x0 = b0 + acc[ai][bj][m][0], x1 = b1 + acc[ai][bj][m][1];
;                     if (out32) { __builtin_nontemporal_store(x0, (f32x4*)(out32 + off + bj * 128)); __builtin_nontemporal_store(x1, (f32x4*)(out32 + off + bj * 128 + 4)); }
;                     else *(u32x4*)(XN + off + bj * 128) = pack8(x0, x1);
.LBB0_965:
	v_cvt_pk_bf16_f32 v92, v76, v77
	v_cvt_pk_bf16_f32 v93, v78, v79
	v_cvt_pk_bf16_f32 v94, v72, v73
	v_cvt_pk_bf16_f32 v95, v74, v75
	global_store_dwordx4 v[84:85], v[92:95], off

; __device__ __forceinline__ u32x4 pack8(f32x4 v0, f32x4 v1) { u32x4 w; w.x = pk2(v0[0], v0[1]); w.y = pk2(v0[2], v0[3]); w.z = pk2(v1[0], v1[1]); w.w = pk2(v1[2], v1[3]); return w; }
;     __device__ __forceinline__ void operator()(const f32x4 (&acc)[2][2][4][2], const Unit& u, int wr, int wc, int fr, int fq) const {
;     ...
;                     else *(u32x4*)(XN + off + bj * 128) = pack8(x0, x1);
;                     ss += ((x0[0] * x0[0] + x0[1] * x0[1]) + (x0[2] * x0[2] + x0[3] * x0[3])) + ((x1[0] * x1[0] + x1[1] * x1[1]) + (x1[2] * x1[2] + x1[3] * x1[3]));
;                 }
;                 ss += __shfl_xor(ss, 16); ss += __shfl_xor(ss, 32);
;                 if (fq == 0) part[(size_t)row * 16 + u.pn * 4 + wc] = ss;
.LBB0_968:
	v_cvt_pk_bf16_f32 v92, v68, v69
	v_cvt_pk_bf16_f32 v93, v70, v71
	v_cvt_pk_bf16_f32 v94, v64, v65
	v_cvt_pk_bf16_f32 v95, v66, v67
	global_store_dwordx4 v[84:85], v[92:95], off offset:256
.LBB0_969:
	v_mul_f32_e32 v77, v77, v77
	v_mul_f32_e32 v73, v73, v73
	v_mul_f32_e32 v69, v69, v69
	v_mul_f32_e32 v65, v65, v65
	v_fmac_f32_e32 v77, v76, v76
	v_mul_f32_e32 v76, v79, v79
	v_fmac_f32_e32 v73, v72, v72
	v_mul_f32_e32 v72, v75, v75
	v_fmac_f32_e32 v69, v68, v68
	v_mul_f32_e32 v68, v71, v71
	v_fmac_f32_e32 v65, v64, v64
	v_mul_f32_e32 v64, v67, v67
	v_fmac_f32_e32 v76, v78, v78
	v_fmac_f32_e32 v72, v74, v74
	v_fmac_f32_e32 v68, v70, v70
	v_fmac_f32_e32 v64, v66, v66
	v_add_f32_e32 v76, v77, v76
	v_add_f32_e32 v72, v73, v72
	v_add_f32_e32 v68, v69, v68
	v_add_f32_e32 v64, v65, v64
	v_add_f32_e32 v72, v76, v72
	v_add_f32_e32 v64, v68, v64
	v_add_f32_e32 v64, v72, v64
	v_mov_b32_e32 v65, v64
	s_nop 1
	v_permlane16_swap_b32_e32 v64, v65
	v_add_f32_e32 v64, v64, v65
	v_mov_b32_e32 v65, v64
	s_nop 1
	v_permlane32_swap_b32_e32 v64, v65
	s_and_saveexec_b64 s[44:45], s[38:39]
	s_cbranch_execz .LBB0_971
	v_lshlrev_b64 v[66:67], 6, v[222:223]
	v_lshl_add_u64 v[66:67], s[62:63], 0, v[66:67]
	v_lshl_add_u64 v[66:67], s[22:23], 2, v[66:67]
	s_lshl_b32 s58, s53, 2
	v_lshl_add_u64 v[66:67], v[66:67], 0, s[58:59]
	s_waitcnt lgkmcnt(0)
	v_add_f32_e32 v64, v64, v65
	global_store_dword v[66:67], v64, off

; __device__ __forceinline__ u32x4 pack8(f32x4 v0, f32x4 v1) { u32x4 w; w.x = pk2(v0[0], v0[1]); w.y = pk2(v0[2], v0[3]); w.z = pk2(v1[0], v1[1]); w.w = pk2(v1[2], v1[3]); return w; }
;     __device__ __forceinline__ void operator()(const f32x4 (&acc)[2][2][4][2], const Unit& u, int wr, int wc, int fr, int fq) const {
;     ...
;                 const int row = row0 + ai * 128 + m * 16; const size_t off = (size_t)row * DM + col0; float ss = 0.f;
; #pragma unroll
;                 for (int bj = 0; bj < 2; ++bj) {
;                     f32x4 b0, b1;
;                     if (base32) { b0 = __builtin_nontemporal_load((const f32x4*)(base32 + off + bj * 128)); b1 = __builtin_nontemporal_load((const f32x4*)(base32 + off + bj * 128 + 4)); }
;                     else { const u32x4 w = bw[ai][m][bj]; b0 = (f32x4){bflo(w.x), bfhi(w.x), bflo(w.y), bfhi(w.y)}; b1 = (f32x4){bflo(w.z), bfhi(w.z), bflo(w.w), bfhi(w.w)}; }
;                     const f32x4 x0 = b0 + acc[ai][bj][m][0], x1 = b1 + acc[ai][bj][m][1];
;                     if (out32) { __builtin_nontemporal_store(x0, (f32x4*)(out32 + off + bj * 128)); __builtin_nontemporal_store(x1, (f32x4*)(out32 + off + bj * 128 + 4)); }
;                     else *(u32x4*)(XN + off + bj * 128) = pack8(x0, x1);
.LBB0_973:
	v_cvt_pk_bf16_f32 v68, v60, v61
	v_cvt_pk_bf16_f32 v69, v62, v63
	v_cvt_pk_bf16_f32 v70, v56, v57
	v_cvt_pk_bf16_f32 v71, v58, v59
	global_store_dwordx4 v[64:65], v[68:71], off

; __device__ __forceinline__ u32x4 pack8(f32x4 v0, f32x4 v1) { u32x4 w; w.x = pk2(v0[0], v0[1]); w.y = pk2(v0[2], v0[3]); w.z = pk2(v1[0], v1[1]); w.w = pk2(v1[2], v1[3]); return w; }
;     __device__ __forceinline__ void operator()(const f32x4 (&acc)[2][2][4][2], const Unit& u, int wr, int wc, int fr, int fq) const {
;     ...
;                     else *(u32x4*)(XN + off + bj * 128) = pack8(x0, x1);
;                     ss += ((x0[0] * x0[0] + x0[1] * x0[1]) + (x0[2] * x0[2] + x0[3] * x0[3])) + ((x1[0] * x1[0] + x1[1] * x1[1]) + (x1[2] * x1[2] + x1[3] * x1[3]));
;                 }
;                 ss += __shfl_xor(ss, 16); ss += __shfl_xor(ss, 32);
;                 if (fq == 0) part[(size_t)row * 16 + u.pn * 4 + wc] = ss;
.LBB0_976:
	v_cvt_pk_bf16_f32 v66, v52, v53
	v_cvt_pk_bf16_f32 v67, v54, v55
	v_cvt_pk_bf16_f32 v68, v48, v49
	v_cvt_pk_bf16_f32 v69, v50, v51
	global_store_dwordx4 v[64:65], v[66:69], off offset:256
.LBB0_977:
	v_mul_f32_e32 v61, v61, v61
	v_mul_f32_e32 v57, v57, v57
	v_mul_f32_e32 v53, v53, v53
	v_mul_f32_e32 v49, v49, v49
	v_fmac_f32_e32 v61, v60, v60
	v_mul_f32_e32 v60, v63, v63
	v_fmac_f32_e32 v57, v56, v56
	v_mul_f32_e32 v56, v59, v59
	v_fmac_f32_e32 v53, v52, v52
	v_mul_f32_e32 v52, v55, v55
	v_fmac_f32_e32 v49, v48, v48
	v_mul_f32_e32 v48, v51, v51
	v_fmac_f32_e32 v60, v62, v62
	v_fmac_f32_e32 v56, v58, v58
	v_fmac_f32_e32 v52, v54, v54
	v_fmac_f32_e32 v48, v50, v50
	v_add_f32_e32 v60, v61, v60
	v_add_f32_e32 v56, v57, v56
	v_add_f32_e32 v52, v53, v52
	v_add_f32_e32 v48, v49, v48
	v_add_f32_e32 v56, v60, v56
	v_add_f32_e32 v48, v52, v48
	v_add_f32_e32 v48, v56, v48
	v_mov_b32_e32 v49, v48
	s_nop 1
	v_permlane16_swap_b32_e32 v48, v49
	v_add_f32_e32 v48, v48, v49
	v_mov_b32_e32 v49, v48
	s_nop 1
	v_permlane32_swap_b32_e32 v48, v49
	s_and_saveexec_b64 s[44:45], s[38:39]
	s_cbranch_execz .LBB0_979
	v_lshlrev_b64 v[50:51], 6, v[220:221]
	v_lshl_add_u64 v[50:51], s[62:63], 0, v[50:51]
	v_lshl_add_u64 v[50:51], s[22:23], 2, v[50:51]
	s_lshl_b32 s58, s53, 2
	v_lshl_add_u64 v[50:51], v[50:51], 0, s[58:59]
	s_waitcnt lgkmcnt(0)
	v_add_f32_e32 v48, v48, v49
	global_store_dword v[50:51], v48, off

; __device__ __forceinline__ u32x4 pack8(f32x4 v0, f32x4 v1) { u32x4 w; w.x = pk2(v0[0], v0[1]); w.y = pk2(v0[2], v0[3]); w.z = pk2(v1[0], v1[1]); w.w = pk2(v1[2], v1[3]); return w; }
;     __device__ __forceinline__ void operator()(const f32x4 (&acc)[2][2][4][2], const Unit& u, int wr, int wc, int fr, int fq) const {
;     ...
;                 const int row = row0 + ai * 128 + m * 16; const size_t off = (size_t)row * DM + col0; float ss = 0.f;
; #pragma unroll
;                 for (int bj = 0; bj < 2; ++bj) {
;                     f32x4 b0, b1;
;                     if (base32) { b0 = __builtin_nontemporal_load((const f32x4*)(base32 + off + bj * 128)); b1 = __builtin_nontemporal_load((const f32x4*)(base32 + off + bj * 128 + 4)); }
;                     else { const u32x4 w = bw[ai][m][bj]; b0 = (f32x4){bflo(w.x), bfhi(w.x), bflo(w.y), bfhi(w.y)}; b1 = (f32x4){bflo(w.z), bfhi(w.z), bflo(w.w), bfhi(w.w)}; }
;                     const f32x4 x0 = b0 + acc[ai][bj][m][0], x1 = b1 + acc[ai][bj][m][1];
;                     if (out32) { __builtin_nontemporal_store(x0, (f32x4*)(out32 + off + bj * 128)); __builtin_nontemporal_store(x1, (f32x4*)(out32 + off + bj * 128 + 4)); }
;                     else *(u32x4*)(XN + off + bj * 128) = pack8(x0, x1);
.LBB0_981:
	v_cvt_pk_bf16_f32 v52, v44, v45
	v_cvt_pk_bf16_f32 v53, v46, v47
	v_cvt_pk_bf16_f32 v54, v40, v41
	v_cvt_pk_bf16_f32 v55, v42, v43
	global_store_dwordx4 v[48:49], v[52:55], off

; __device__ __forceinline__ u32x4 pack8(f32x4 v0, f32x4 v1) { u32x4 w; w.x = pk2(v0[0], v0[1]); w.y = pk2(v0[2], v0[3]); w.z = pk2(v1[0], v1[1]); w.w = pk2(v1[2], v1[3]); return w; }
;     __device__ __forceinline__ void operator()(const f32x4 (&acc)[2][2][4][2], const Unit& u, int wr, int wc, int fr, int fq) const {
;     ...
;                     else *(u32x4*)(XN + off + bj * 128) = pack8(x0, x1);
;                     ss += ((x0[0] * x0[0] + x0[1] * x0[1]) + (x0[2] * x0[2] + x0[3] * x0[3])) + ((x1[0] * x1[0] + x1[1] * x1[1]) + (x1[2] * x1[2] + x1[3] * x1[3]));
;                 }
;                 ss += __shfl_xor(ss, 16); ss += __shfl_xor(ss, 32);
;                 if (fq == 0) part[(size_t)row * 16 + u.pn * 4 + wc] = ss;
.LBB0_984:
	v_cvt_pk_bf16_f32 v50, v36, v37
	v_cvt_pk_bf16_f32 v51, v38, v39
	v_cvt_pk_bf16_f32 v52, v32, v33
	v_cvt_pk_bf16_f32 v53, v34, v35
	global_store_dwordx4 v[48:49], v[50:53], off offset:256
.LBB0_985:
	v_mul_f32_e32 v45, v45, v45
	v_mul_f32_e32 v41, v41, v41
	v_mul_f32_e32 v37, v37, v37
	v_mul_f32_e32 v33, v33, v33
	v_fmac_f32_e32 v45, v44, v44
	v_mul_f32_e32 v44, v47, v47
	v_fmac_f32_e32 v41, v40, v40
	v_mul_f32_e32 v40, v43, v43
	v_fmac_f32_e32 v37, v36, v36
	v_mul_f32_e32 v36, v39, v39
	v_fmac_f32_e32 v33, v32, v32
	v_mul_f32_e32 v32, v35, v35
	v_fmac_f32_e32 v44, v46, v46
	v_fmac_f32_e32 v40, v42, v42
	v_fmac_f32_e32 v36, v38, v38
	v_fmac_f32_e32 v32, v34, v34
	v_add_f32_e32 v44, v45, v44
	v_add_f32_e32 v40, v41, v40
	v_add_f32_e32 v36, v37, v36
	v_add_f32_e32 v32, v33, v32
	v_add_f32_e32 v40, v44, v40
	v_add_f32_e32 v32, v36, v32
	v_add_f32_e32 v32, v40, v32
	v_mov_b32_e32 v33, v32
	s_nop 1
	v_permlane16_swap_b32_e32 v32, v33
	v_add_f32_e32 v32, v32, v33
	v_mov_b32_e32 v33, v32
	s_nop 1
	v_permlane32_swap_b32_e32 v32, v33
	s_and_saveexec_b64 s[44:45], s[38:39]
	s_cbranch_execz .LBB0_987
	v_lshlrev_b64 v[34:35], 6, v[218:219]
	v_lshl_add_u64 v[34:35], s[62:63], 0, v[34:35]
	v_lshl_add_u64 v[34:35], s[22:23], 2, v[34:35]
	s_lshl_b32 s58, s53, 2
	v_lshl_add_u64 v[34:35], v[34:35], 0, s[58:59]
	s_waitcnt lgkmcnt(0)
	v_add_f32_e32 v32, v32, v33
	global_store_dword v[34:35], v32, off

; __device__ __forceinline__ u32x4 pack8(f32x4 v0, f32x4 v1) { u32x4 w; w.x = pk2(v0[0], v0[1]); w.y = pk2(v0[2], v0[3]); w.z = pk2(v1[0], v1[1]); w.w = pk2(v1[2], v1[3]); return w; }
;     __device__ __forceinline__ void operator()(const f32x4 (&acc)[2][2][4][2], const Unit& u, int wr, int wc, int fr, int fq) const {
;     ...
;                 const int row = row0 + ai * 128 + m * 16; const size_t off = (size_t)row * DM + col0; float ss = 0.f;
; #pragma unroll
;                 for (int bj = 0; bj < 2; ++bj) {
;                     f32x4 b0, b1;
;                     if (base32) { b0 = __builtin_nontemporal_load((const f32x4*)(base32 + off + bj * 128)); b1 = __builtin_nontemporal_load((const f32x4*)(base32 + off + bj * 128 + 4)); }
;                     else { const u32x4 w = bw[ai][m][bj]; b0 = (f32x4){bflo(w.x), bfhi(w.x), bflo(w.y), bfhi(w.y)}; b1 = (f32x4){bflo(w.z), bfhi(w.z), bflo(w.w), bfhi(w.w)}; }
;                     const f32x4 x0 = b0 + acc[ai][bj][m][0], x1 = b1 + acc[ai][bj][m][1];
;                     if (out32) { __builtin_nontemporal_store(x0, (f32x4*)(out32 + off + bj * 128)); __builtin_nontemporal_store(x1, (f32x4*)(out32 + off + bj * 128 + 4)); }
;                     else *(u32x4*)(XN + off + bj * 128) = pack8(x0, x1);
.LBB0_989:
	v_cvt_pk_bf16_f32 v36, v28, v29
	v_cvt_pk_bf16_f32 v37, v30, v31
	v_cvt_pk_bf16_f32 v38, v24, v25
	v_cvt_pk_bf16_f32 v39, v26, v27
	global_store_dwordx4 v[32:33], v[36:39], off

; __device__ __forceinline__ u32x4 pack8(f32x4 v0, f32x4 v1) { u32x4 w; w.x = pk2(v0[0], v0[1]); w.y = pk2(v0[2], v0[3]); w.z = pk2(v1[0], v1[1]); w.w = pk2(v1[2], v1[3]); return w; }
;     __device__ __forceinline__ void operator()(const f32x4 (&acc)[2][2][4][2], const Unit& u, int wr, int wc, int fr, int fq) const {
;     ...
;                     else *(u32x4*)(XN + off + bj * 128) = pack8(x0, x1);
;                     ss += ((x0[0] * x0[0] + x0[1] * x0[1]) + (x0[2] * x0[2] + x0[3] * x0[3])) + ((x1[0] * x1[0] + x1[1] * x1[1]) + (x1[2] * x1[2] + x1[3] * x1[3]));
;                 }
;                 ss += __shfl_xor(ss, 16); ss += __shfl_xor(ss, 32);
;                 if (fq == 0) part[(size_t)row * 16 + u.pn * 4 + wc] = ss;
.LBB0_992:
	v_cvt_pk_bf16_f32 v34, v20, v21
	v_cvt_pk_bf16_f32 v35, v22, v23
	v_cvt_pk_bf16_f32 v36, v16, v17
	v_cvt_pk_bf16_f32 v37, v18, v19
	global_store_dwordx4 v[32:33], v[34:37], off offset:256
.LBB0_993:
	v_mul_f32_e32 v29, v29, v29
	v_mul_f32_e32 v25, v25, v25
	v_mul_f32_e32 v21, v21, v21
	v_mul_f32_e32 v17, v17, v17
	v_fmac_f32_e32 v29, v28, v28
	v_mul_f32_e32 v28, v31, v31
	v_fmac_f32_e32 v25, v24, v24
	v_mul_f32_e32 v24, v27, v27
	v_fmac_f32_e32 v21, v20, v20
	v_mul_f32_e32 v20, v23, v23
	v_fmac_f32_e32 v17, v16, v16
	v_mul_f32_e32 v16, v19, v19
	v_fmac_f32_e32 v28, v30, v30
	v_fmac_f32_e32 v24, v26, v26
	v_fmac_f32_e32 v20, v22, v22
	v_fmac_f32_e32 v16, v18, v18
	v_add_f32_e32 v28, v29, v28
	v_add_f32_e32 v24, v25, v24
	v_add_f32_e32 v20, v21, v20
	v_add_f32_e32 v16, v17, v16
	v_add_f32_e32 v24, v28, v24
	v_add_f32_e32 v16, v20, v16
	v_add_f32_e32 v16, v24, v16
	v_mov_b32_e32 v17, v16
	s_nop 1
	v_permlane16_swap_b32_e32 v16, v17
	v_add_f32_e32 v16, v16, v17
	v_mov_b32_e32 v17, v16
	s_nop 1
	v_permlane32_swap_b32_e32 v16, v17
	s_and_saveexec_b64 s[44:45], s[38:39]
	s_cbranch_execz .LBB0_995
	v_lshlrev_b64 v[18:19], 6, v[216:217]
	v_lshl_add_u64 v[18:19], s[62:63], 0, v[18:19]
	v_lshl_add_u64 v[18:19], s[22:23], 2, v[18:19]
	s_lshl_b32 s58, s53, 2
	v_lshl_add_u64 v[18:19], v[18:19], 0, s[58:59]
	s_waitcnt lgkmcnt(0)
	v_add_f32_e32 v16, v16, v17
	global_store_dword v[18:19], v16, off

; __device__ __forceinline__ u32x4 pack8(f32x4 v0, f32x4 v1) { u32x4 w; w.x = pk2(v0[0], v0[1]); w.y = pk2(v0[2], v0[3]); w.z = pk2(v1[0], v1[1]); w.w = pk2(v1[2], v1[3]); return w; }
;     __device__ __forceinline__ void operator()(const f32x4 (&acc)[2][2][4][2], const Unit& u, int wr, int wc, int fr, int fq) const {
;     ...
;                 const int row = row0 + ai * 128 + m * 16; const size_t off = (size_t)row * DM + col0; float ss = 0.f;
; #pragma unroll
;                 for (int bj = 0; bj < 2; ++bj) {
;                     f32x4 b0, b1;
;                     if (base32) { b0 = __builtin_nontemporal_load((const f32x4*)(base32 + off + bj * 128)); b1 = __builtin_nontemporal_load((const f32x4*)(base32 + off + bj * 128 + 4)); }
;                     else { const u32x4 w = bw[ai][m][bj]; b0 = (f32x4){bflo(w.x), bfhi(w.x), bflo(w.y), bfhi(w.y)}; b1 = (f32x4){bflo(w.z), bfhi(w.z), bflo(w.w), bfhi(w.w)}; }
;                     const f32x4 x0 = b0 + acc[ai][bj][m][0], x1 = b1 + acc[ai][bj][m][1];
;                     if (out32) { __builtin_nontemporal_store(x0, (f32x4*)(out32 + off + bj * 128)); __builtin_nontemporal_store(x1, (f32x4*)(out32 + off + bj * 128 + 4)); }
;                     else *(u32x4*)(XN + off + bj * 128) = pack8(x0, x1);
.LBB0_997:
	v_cvt_pk_bf16_f32 v20, v12, v13
	v_cvt_pk_bf16_f32 v21, v14, v15
	v_cvt_pk_bf16_f32 v22, v8, v9
	v_cvt_pk_bf16_f32 v23, v10, v11
	global_store_dwordx4 v[16:17], v[20:23], off

; __device__ __forceinline__ u32x4 pack8(f32x4 v0, f32x4 v1) { u32x4 w; w.x = pk2(v0[0], v0[1]); w.y = pk2(v0[2], v0[3]); w.z = pk2(v1[0], v1[1]); w.w = pk2(v1[2], v1[3]); return w; }
;     __device__ __forceinline__ void operator()(const f32x4 (&acc)[2][2][4][2], const Unit& u, int wr, int wc, int fr, int fq) const {
;     ...
;                     else *(u32x4*)(XN + off + bj * 128) = pack8(x0, x1);
;                     ss += ((x0[0] * x0[0] + x0[1] * x0[1]) + (x0[2] * x0[2] + x0[3] * x0[3])) + ((x1[0] * x1[0] + x1[1] * x1[1]) + (x1[2] * x1[2] + x1[3] * x1[3]));
;                 }
;                 ss += __shfl_xor(ss, 16); ss += __shfl_xor(ss, 32);
;                 if (fq == 0) part[(size_t)row * 16 + u.pn * 4 + wc] = ss;
.LBB0_1000:
	v_cvt_pk_bf16_f32 v18, v4, v5
	v_cvt_pk_bf16_f32 v19, v6, v7
	v_cvt_pk_bf16_f32 v20, v0, v1
	v_cvt_pk_bf16_f32 v21, v2, v3
	global_store_dwordx4 v[16:17], v[18:21], off offset:256
.LBB0_1001:
	v_mul_f32_e32 v13, v13, v13
	v_mul_f32_e32 v9, v9, v9
	v_mul_f32_e32 v5, v5, v5
	v_mul_f32_e32 v1, v1, v1
	v_fmac_f32_e32 v13, v12, v12
	v_mul_f32_e32 v12, v15, v15
	v_fmac_f32_e32 v9, v8, v8
	v_mul_f32_e32 v8, v11, v11
	v_fmac_f32_e32 v5, v4, v4
	v_mul_f32_e32 v4, v7, v7
	v_fmac_f32_e32 v1, v0, v0
	v_mul_f32_e32 v0, v3, v3
	v_fmac_f32_e32 v12, v14, v14
	v_fmac_f32_e32 v8, v10, v10
	v_fmac_f32_e32 v4, v6, v6
	v_fmac_f32_e32 v0, v2, v2
	v_add_f32_e32 v12, v13, v12
	v_add_f32_e32 v8, v9, v8
	v_add_f32_e32 v4, v5, v4
	v_add_f32_e32 v0, v1, v0
	v_add_f32_e32 v8, v12, v8
	v_add_f32_e32 v0, v4, v0
	v_add_f32_e32 v0, v8, v0
	v_mov_b32_e32 v1, v0
	s_nop 1
	v_permlane16_swap_b32_e32 v0, v1
	v_add_f32_e32 v0, v0, v1
	v_mov_b32_e32 v1, v0
	s_nop 1
	v_permlane32_swap_b32_e32 v0, v1
	s_and_saveexec_b64 s[42:43], s[38:39]
	s_cbranch_execz .LBB0_1003
	v_lshlrev_b64 v[2:3], 6, v[198:199]
	v_lshl_add_u64 v[2:3], s[62:63], 0, v[2:3]
	v_lshl_add_u64 v[2:3], s[22:23], 2, v[2:3]
	s_lshl_b32 s58, s53, 2
	v_lshl_add_u64 v[2:3], v[2:3], 0, s[58:59]
	s_waitcnt lgkmcnt(0)
	v_add_f32_e32 v0, v0, v1
	global_store_dword v[2:3], v0, off
